# removed vmcnt(0) drain before tile-prologue DMAs in GEMM tiles and attention items (loop-top counted waits cover older ops)
# speedup vs baseline: 1.0502x; 1.0018x over previous
; template <int N> DI void wait_vmcnt() { asm volatile("s_waitcnt vmcnt(%0)" ::"n"(N) : "memory"); }
;     ...
;   const int tid = threadIdx.x, lane = tid & 63, w = __builtin_amdgcn_readfirstlane(tid >> 6), wm = w >> 1, wn = w & 1;
; #pragma unroll
;   for (int i = 0; i < TM; i++)
; #pragma unroll
;     for (int j = 0; j < NJ; j++) acc[i][j] = f32x4{0.f, 0.f, 0.f, 0.f};
;   const u16* ga[NIA];
;   const u16* gb[NIB];
; #pragma unroll
;   for (int ii = 0; ii < NIA; ii++) {
;     int r = (w * NIA + ii) * 8 + (lane >> 3), c = (lane & 7) ^ ((r >> 1) & 7);
;     ga[ii] = A + (size_t)(m0 + r) * 1024 + c * 8;
;   }
; #pragma unroll
;   for (int ii = 0; ii < NIB; ii++) {
;     int r = (w * NIB + ii) * 8 + (lane >> 3), c = (lane & 7) ^ ((r >> 1) & 7);
;     gb[ii] = brow(r) + c * 8;
;   }
;   auto glds = [&](int kt, int st) {
;     char* da = smem + st * STAGE + w * (NIA * 1024);
;     char* db = smem + st * STAGE + BM * 128 + w * (NIB * 1024);
; #pragma unroll
;     for (int ii = 0; ii < NIA; ii++) __builtin_amdgcn_global_load_lds((const unsigned*)(ga[ii] + kt * 64), (unsigned*)(da + ii * 1024), 16, 0, 0);
; #pragma unroll
;     for (int ii = 0; ii < NIB; ii++) __builtin_amdgcn_global_load_lds((const unsigned*)(gb[ii] + kt * 64), (unsigned*)(db + ii * 1024), 16, 0, 0);
;   };
;   const int l15 = lane & 15, l4 = lane >> 4;
;   const int swz = (l15 >> 1) & 7;
;   __syncthreads();
;   wait_vmcnt<0>();
;   glds(0, 0);
;   if (NST == 3) glds(1, 1);
; DI void phase1(const P& p, char* smem, int bid, int nb) {
;   for (int t = bid; t < 128 * 24; t += nb) phase1_tile<4>(p, smem, (t / 24) * 256, (t % 24) * 128);
.LBB0_45:
	s_mul_hi_i32 s2, s38, 0x2aaaaaab
	s_lshr_b32 s3, s2, 31
	s_ashr_i32 s2, s2, 2
	s_add_i32 s2, s2, s3
	s_mul_i32 s3, s2, 24
	s_sub_i32 s3, s38, s3
	s_lshl_b32 s18, s3, 7
	v_readfirstlane_b32 s3, v1
	s_lshr_b32 s29, s3, 6
	s_lshl_b32 s41, s29, 5
	s_lshl_b32 s28, s2, 8
	v_or_b32_e32 v8, s41, v187
	v_add_u32_e32 v2, s28, v8
	v_ashrrev_i32_e32 v3, 31, v2
	s_load_dwordx16 s[44:59], s[0:1], 0x98
	v_lshlrev_b64 v[4:5], 11, v[2:3]
	v_or_b32_e32 v3, 8, v8
	v_lshrrev_b32_e32 v14, 1, v3
	v_add_u32_e32 v6, s28, v3
	v_or_b32_e32 v8, 24, v8
	v_xor_b32_e32 v9, v14, v1
	v_ashrrev_i32_e32 v7, 31, v6
	v_lshrrev_b32_e32 v15, 1, v8
	s_lshl_b32 s42, s29, 4
	v_lshlrev_b64 v[6:7], 11, v[6:7]
	v_lshlrev_b32_e32 v3, 4, v9
	v_xor_b32_e32 v10, v15, v1
	v_add_u32_e32 v8, s28, v8
	v_or_b32_e32 v12, s42, v187
	s_lshl_b32 s39, s29, 12
	s_waitcnt lgkmcnt(0)
	v_lshl_add_u64 v[6:7], s[56:57], 0, v[6:7]
	v_and_b32_e32 v68, 0x70, v3
	v_or_b32_e32 v2, 16, v2
	v_ashrrev_i32_e32 v9, 31, v8
	v_lshlrev_b32_e32 v10, 4, v10
	v_lshrrev_b32_e32 v16, 1, v12
	s_add_i32 s43, s39, 0
	v_lshl_add_u64 v[4:5], v[70:71], 0, v[4:5]
	v_lshl_add_u64 v[6:7], v[6:7], 0, v[68:69]
	v_ashrrev_i32_e32 v3, 31, v2
	v_lshlrev_b64 v[8:9], 11, v[8:9]
	v_and_b32_e32 v68, 0x70, v10
	v_xor_b32_e32 v13, v16, v1
	v_add_u32_e32 v10, s18, v12
	v_or_b32_e32 v12, 8, v12
	s_barrier
	s_nop 0
	s_mov_b32 m0, s43
	v_lshlrev_b64 v[2:3], 11, v[2:3]
	v_lshl_add_u64 v[8:9], s[56:57], 0, v[8:9]
	v_ashrrev_i32_e32 v11, 31, v10
	v_lshlrev_b32_e32 v13, 4, v13
	v_lshrrev_b32_e32 v17, 1, v12
	v_add_u32_e32 v12, s18, v12
	global_load_lds_dwordx4 v[4:5], off
	s_add_i32 m0, s43, 0x400
	v_lshl_add_u64 v[2:3], v[70:71], 0, v[2:3]
	v_lshl_add_u64 v[8:9], v[8:9], 0, v[68:69]
	v_lshlrev_b64 v[10:11], 11, v[10:11]
	v_and_b32_e32 v68, 0x70, v13
	v_xor_b32_e32 v18, v17, v1
	v_ashrrev_i32_e32 v13, 31, v12
	s_lshl_b32 s40, s29, 11
	global_load_lds_dwordx4 v[6:7], off
	s_add_i32 m0, s43, 0x800
	v_lshl_add_u64 v[10:11], s[58:59], 0, v[10:11]
	v_lshlrev_b64 v[12:13], 11, v[12:13]
	v_lshlrev_b32_e32 v18, 4, v18
	global_load_lds_dwordx4 v[2:3], off
	s_add_i32 m0, s43, 0xc00
	s_sub_i32 s29, s43, s40
	v_lshl_add_u64 v[10:11], v[10:11], 0, v[68:69]
	v_lshl_add_u64 v[12:13], s[58:59], 0, v[12:13]
	v_and_b32_e32 v68, 0x70, v18
	global_load_lds_dwordx4 v[8:9], off
	s_add_i32 m0, s29, 0x8000
	v_lshl_add_u64 v[12:13], v[12:13], 0, v[68:69]
	global_load_lds_dwordx4 v[10:11], off
	s_add_i32 m0, s29, 0x8400
	v_lshl_add_u64 v[4:5], v[4:5], 0, s[16:17]
	global_load_lds_dwordx4 v[12:13], off
	s_add_i32 m0, s43, 0xc000
	v_lshl_add_u64 v[2:3], v[2:3], 0, s[16:17]
	global_load_lds_dwordx4 v[4:5], off
	v_lshl_add_u64 v[4:5], v[6:7], 0, s[16:17]
	s_add_i32 m0, s43, 0xc400
	s_add_i32 s29, s40, 0
	global_load_lds_dwordx4 v[4:5], off
	s_add_i32 m0, s43, 0xc800
	s_and_b32 s19, s3, 64
	global_load_lds_dwordx4 v[2:3], off
	v_lshl_add_u64 v[2:3], v[8:9], 0, s[16:17]
	s_add_i32 m0, s43, 0xcc00
	s_add_i32 s41, s41, s28
	global_load_lds_dwordx4 v[2:3], off
	s_add_i32 m0, s29, 0x14000
	v_lshl_add_u64 v[2:3], v[10:11], 0, s[16:17]
	global_load_lds_dwordx4 v[2:3], off
	v_lshl_add_u64 v[2:3], v[12:13], 0, s[16:17]
	s_add_i32 m0, s29, 0x14400
	s_lshr_b32 s29, s3, 1
	global_load_lds_dwordx4 v[2:3], off
	s_and_b32 s3, s29, 0x1ffffc0
	v_or_b32_e32 v2, s3, v195
	v_or_b32_e32 v3, s19, v195
	v_lshlrev_b32_e32 v97, 7, v2
	v_or_b32_e32 v2, s41, v187
	v_lshlrev_b32_e32 v68, 7, v3
	v_ashrrev_i32_e32 v3, 31, v2
	v_lshlrev_b64 v[2:3], 11, v[2:3]
	v_lshl_add_u64 v[74:75], v[72:73], 0, v[2:3]
	v_or_b32_e32 v2, s41, v94
	v_ashrrev_i32_e32 v3, 31, v2
	v_lshlrev_b64 v[2:3], 11, v[2:3]
	v_bitop3_b32 v4, v14, 7, v1 bitop3:0x48
	v_lshl_or_b32 v2, v4, 4, v2
	v_lshl_add_u64 v[76:77], s[12:13], 0, v[2:3]
	v_or_b32_e32 v2, s41, v95
	v_ashrrev_i32_e32 v3, 31, v2
	v_lshlrev_b64 v[2:3], 11, v[2:3]
	v_lshl_add_u64 v[78:79], v[72:73], 0, v[2:3]
	v_or_b32_e32 v2, s41, v96
	v_ashrrev_i32_e32 v3, 31, v2
	v_lshlrev_b64 v[2:3], 11, v[2:3]
	v_bitop3_b32 v4, v15, 7, v1 bitop3:0x48
	s_lshl_b32 s3, s38, 7
	v_lshl_or_b32 v2, v4, 4, v2
	s_add_i32 s42, s42, s3
	v_lshl_add_u64 v[80:81], s[12:13], 0, v[2:3]
	v_or_b32_e32 v2, s42, v187
	s_mulk_i32 s2, 0xc00
	v_subrev_u32_e32 v2, s2, v2
	v_ashrrev_i32_e32 v3, 31, v2
	v_lshlrev_b64 v[2:3], 11, v[2:3]
	v_bitop3_b32 v4, v16, 7, v1 bitop3:0x48
	v_lshl_or_b32 v2, v4, 4, v2
	v_lshl_add_u64 v[82:83], s[14:15], 0, v[2:3]
	v_or_b32_e32 v2, s42, v94
	v_subrev_u32_e32 v2, s2, v2
	v_ashrrev_i32_e32 v3, 31, v2
	v_lshlrev_b64 v[2:3], 11, v[2:3]
	v_bitop3_b32 v4, v17, 7, v1 bitop3:0x48
	v_lshl_or_b32 v2, v4, 4, v2
	v_lshl_add_u64 v[84:85], s[14:15], 0, v[2:3]
	s_mov_b32 s41, 0
	s_mov_b64 s[2:3], 0
	v_mov_b32_e32 v2, 0
	v_mov_b32_e32 v3, v69
	v_mov_b32_e32 v4, v69
	v_mov_b32_e32 v5, v69
	v_mov_b32_e32 v6, 0
	v_mov_b32_e32 v7, v69
	v_mov_b32_e32 v8, v69
	v_mov_b32_e32 v9, v69
	v_mov_b32_e32 v10, 0
	v_mov_b32_e32 v11, v69
	v_mov_b32_e32 v12, v69
	v_mov_b32_e32 v13, v69
	v_mov_b32_e32 v14, 0
	v_mov_b32_e32 v15, v69
	v_mov_b32_e32 v16, v69
	v_mov_b32_e32 v17, v69
	v_mov_b32_e32 v18, 0
	v_mov_b32_e32 v19, v69
	v_mov_b32_e32 v20, v69
	v_mov_b32_e32 v21, v69
	v_mov_b32_e32 v22, 0
	v_mov_b32_e32 v23, v69
	v_mov_b32_e32 v24, v69
	v_mov_b32_e32 v25, v69
	v_mov_b32_e32 v26, 0
	v_mov_b32_e32 v27, v69
	v_mov_b32_e32 v28, v69
	v_mov_b32_e32 v29, v69
	v_mov_b32_e32 v30, 0
	v_mov_b32_e32 v31, v69
	v_mov_b32_e32 v32, v69
	v_mov_b32_e32 v33, v69
	v_mov_b32_e32 v34, 0
	v_mov_b32_e32 v35, v69
	v_mov_b32_e32 v36, v69
	v_mov_b32_e32 v37, v69
	v_mov_b32_e32 v38, 0
	v_mov_b32_e32 v39, v69
	v_mov_b32_e32 v40, v69
	v_mov_b32_e32 v41, v69
	v_mov_b32_e32 v42, 0
	v_mov_b32_e32 v43, v69
	v_mov_b32_e32 v44, v69
	v_mov_b32_e32 v45, v69
	v_mov_b32_e32 v46, 0
	v_mov_b32_e32 v47, v69
	v_mov_b32_e32 v48, v69
	v_mov_b32_e32 v49, v69
	v_mov_b32_e32 v50, 0
	v_mov_b32_e32 v51, v69
	v_mov_b32_e32 v52, v69
	v_mov_b32_e32 v53, v69
	v_mov_b32_e32 v54, 0
	v_mov_b32_e32 v55, v69
	v_mov_b32_e32 v56, v69
	v_mov_b32_e32 v57, v69
	v_mov_b32_e32 v58, 0
	v_mov_b32_e32 v59, v69
	v_mov_b32_e32 v60, v69
	v_mov_b32_e32 v61, v69
	v_mov_b32_e32 v62, 0
	v_mov_b32_e32 v63, v69
	v_mov_b32_e32 v64, v69
	v_mov_b32_e32 v65, v69

; template <int N> DI void wait_vmcnt() { asm volatile("s_waitcnt vmcnt(%0)" ::"n"(N) : "memory"); }
;     ...
;   const int tid = threadIdx.x, lane = tid & 63, w = __builtin_amdgcn_readfirstlane(tid >> 6), wm = w >> 1, wn = w & 1;
; #pragma unroll
;   for (int i = 0; i < TM; i++)
; #pragma unroll
;     for (int j = 0; j < NJ; j++) acc[i][j] = f32x4{0.f, 0.f, 0.f, 0.f};
;   const u16* ga[NIA];
;   const u16* gb[NIB];
; #pragma unroll
;   for (int ii = 0; ii < NIA; ii++) {
;     int r = (w * NIA + ii) * 8 + (lane >> 3), c = (lane & 7) ^ ((r >> 1) & 7);
;     ga[ii] = A + (size_t)(m0 + r) * 1024 + c * 8;
;   }
; #pragma unroll
;   for (int ii = 0; ii < NIB; ii++) {
;     int r = (w * NIB + ii) * 8 + (lane >> 3), c = (lane & 7) ^ ((r >> 1) & 7);
;     gb[ii] = brow(r) + c * 8;
;   }
;   auto glds = [&](int kt, int st) {
;     char* da = smem + st * STAGE + w * (NIA * 1024);
;     char* db = smem + st * STAGE + BM * 128 + w * (NIB * 1024);
; #pragma unroll
;     for (int ii = 0; ii < NIA; ii++) __builtin_amdgcn_global_load_lds((const unsigned*)(ga[ii] + kt * 64), (unsigned*)(da + ii * 1024), 16, 0, 0);
; #pragma unroll
;     for (int ii = 0; ii < NIB; ii++) __builtin_amdgcn_global_load_lds((const unsigned*)(gb[ii] + kt * 64), (unsigned*)(db + ii * 1024), 16, 0, 0);
;   };
;   const int l15 = lane & 15, l4 = lane >> 4;
;   const int swz = (l15 >> 1) & 7;
;   __syncthreads();
;   wait_vmcnt<0>();
;   glds(0, 0);
;   if (NST == 3) glds(1, 1);
; template <int TM>
; DI void phase4_tile(const P& p, char* smem, int m0, int nt) {
;     ...
;   {
;     const u16* wbase = WT + (size_t)(C_FQ + nt * 128) * 1024;
;     auto brow = [&](int r) { return wbase + (size_t)r * 1024; };
;     f32x4 acc[TM][4];
;     if (nt < 16) {
;       gemm_main<128, false, true, 4, decltype(brow), TM>(XN, m0, brow, smem, acc);
.LBB0_521:
	s_ashr_i32 s0, s5, 31
	s_lshr_b32 s0, s0, 29
	s_add_i32 s0, s5, s0
	s_ashr_i32 s52, s0, 3
	s_and_b32 s0, s0, 0x1fffff8
	s_sub_i32 s0, s5, s0
	s_lshl_b32 s13, s0, 7
	v_readlane_b32 s36, v251, 1
	v_readfirstlane_b32 s15, v188
	s_add_i32 s0, s13, 0x1010
	v_readlane_b32 s50, v251, 15
	v_readlane_b32 s51, v251, 16
	s_lshl_b32 s17, s52, 8
	s_lshr_b32 s33, s15, 6
	s_lshl_b64 s[30:31], s[0:1], 11
	v_readlane_b32 s48, v251, 13
	v_readlane_b32 s49, v251, 14
	s_mov_b64 s[66:67], s[50:51]
	s_add_u32 s30, s66, s30
	s_addc_u32 s31, s67, s31
	s_lshl_b32 s0, s33, 5
	v_or_b32_e32 v8, s0, v1
	v_add_u32_e32 v2, s17, v8
	v_ashrrev_i32_e32 v3, 31, v2
	v_lshlrev_b64 v[4:5], 11, v[2:3]
	v_or_b32_e32 v3, 8, v8
	v_lshrrev_b32_e32 v16, 1, v3
	v_add_u32_e32 v6, s17, v3
	v_or_b32_e32 v8, 24, v8
	v_xor_b32_e32 v9, v16, v188
	v_ashrrev_i32_e32 v7, 31, v6
	v_lshrrev_b32_e32 v17, 1, v8
	v_add_u32_e32 v8, s17, v8
	s_mov_b64 s[64:65], s[48:49]
	v_lshlrev_b64 v[6:7], 11, v[6:7]
	v_lshlrev_b32_e32 v3, 4, v9
	v_xor_b32_e32 v10, v17, v188
	v_ashrrev_i32_e32 v9, 31, v8
	v_lshl_add_u64 v[6:7], s[64:65], 0, v[6:7]
	v_and_b32_e32 v68, 0x70, v3
	v_lshlrev_b64 v[8:9], 11, v[8:9]
	v_lshlrev_b32_e32 v10, 4, v10
	v_lshl_add_u64 v[6:7], v[6:7], 0, v[68:69]
	v_lshl_add_u64 v[8:9], s[64:65], 0, v[8:9]
	v_and_b32_e32 v68, 0x70, v10
	s_lshl_b32 s53, s33, 4
	v_lshl_add_u64 v[8:9], v[8:9], 0, v[68:69]
	v_or_b32_e32 v68, s53, v1
	v_lshrrev_b32_e32 v18, 1, v68
	v_xor_b32_e32 v14, v18, v188
	v_lshlrev_b64 v[10:11], 11, v[68:69]
	v_lshlrev_b32_e32 v14, 4, v14
	v_lshl_add_u64 v[12:13], s[30:31], 0, v[10:11]
	v_and_b32_e32 v14, 0x70, v14
	v_mov_b32_e32 v15, v69
	v_or_b32_e32 v68, 8, v68
	v_lshl_add_u64 v[12:13], v[12:13], 0, v[14:15]
	v_lshlrev_b64 v[14:15], 11, v[68:69]
	s_lshl_b32 s34, s33, 12
	v_or_b32_e32 v2, 16, v2
	v_lshl_add_u64 v[14:15], s[30:31], 0, v[14:15]
	s_add_i32 s30, s34, 0
	v_lshl_add_u64 v[4:5], v[70:71], 0, v[4:5]
	v_ashrrev_i32_e32 v3, 31, v2
	s_barrier
	s_nop 0
	s_mov_b32 m0, s30
	v_lshlrev_b64 v[2:3], 11, v[2:3]
	v_lshrrev_b32_e32 v19, 1, v68
	global_load_lds_dwordx4 v[4:5], off
	s_add_i32 m0, s30, 0x400
	v_lshl_add_u64 v[2:3], v[70:71], 0, v[2:3]
	v_xor_b32_e32 v20, v19, v188
	s_lshl_b32 s35, s33, 11
	global_load_lds_dwordx4 v[6:7], off
	s_add_i32 m0, s30, 0x800
	v_lshlrev_b32_e32 v20, 4, v20
	global_load_lds_dwordx4 v[2:3], off
	s_add_i32 m0, s30, 0xc00
	s_sub_i32 s31, s30, s35
	v_and_b32_e32 v68, 0x70, v20
	global_load_lds_dwordx4 v[8:9], off
	s_add_i32 m0, s31, 0x8000
	v_lshl_add_u64 v[14:15], v[14:15], 0, v[68:69]
	global_load_lds_dwordx4 v[12:13], off
	s_add_i32 m0, s31, 0x8400
	v_lshl_add_u64 v[4:5], v[4:5], 0, s[10:11]
	global_load_lds_dwordx4 v[14:15], off
	s_add_i32 m0, s30, 0xc000
	v_lshl_add_u64 v[2:3], v[2:3], 0, s[10:11]
	global_load_lds_dwordx4 v[4:5], off
	v_lshl_add_u64 v[4:5], v[6:7], 0, s[10:11]
	s_add_i32 m0, s30, 0xc400
	s_lshr_b32 s33, s15, 1
	global_load_lds_dwordx4 v[4:5], off
	s_add_i32 m0, s30, 0xc800
	s_and_b32 s15, s15, 64
	global_load_lds_dwordx4 v[2:3], off
	v_lshl_add_u64 v[2:3], v[8:9], 0, s[10:11]
	s_add_i32 m0, s30, 0xcc00
	s_add_i32 s30, s35, 0
	global_load_lds_dwordx4 v[2:3], off
	s_add_i32 m0, s30, 0x14000
	v_lshl_add_u64 v[2:3], v[12:13], 0, s[10:11]
	global_load_lds_dwordx4 v[2:3], off
	v_lshl_add_u64 v[2:3], v[14:15], 0, s[10:11]
	s_add_i32 m0, s30, 0x14400
	s_and_b32 s30, s33, 0x1ffffc0
	global_load_lds_dwordx4 v[2:3], off
	v_or_b32_e32 v2, s30, v195
	s_add_i32 s0, s0, s17
	v_or_b32_e32 v3, s15, v195
	v_lshlrev_b32_e32 v99, 7, v2
	v_or_b32_e32 v2, s0, v1
	v_lshlrev_b32_e32 v98, 7, v3
	v_ashrrev_i32_e32 v3, 31, v2
	v_lshlrev_b64 v[2:3], 11, v[2:3]
	v_lshl_add_u64 v[74:75], v[72:73], 0, v[2:3]
	v_or_b32_e32 v2, s0, v94
	v_ashrrev_i32_e32 v3, 31, v2
	v_lshlrev_b64 v[2:3], 11, v[2:3]
	v_bitop3_b32 v4, v16, 7, v188 bitop3:0x48
	v_lshl_or_b32 v2, v4, 4, v2
	v_lshl_add_u64 v[76:77], s[6:7], 0, v[2:3]
	v_or_b32_e32 v2, s0, v95
	v_ashrrev_i32_e32 v3, 31, v2
	v_lshlrev_b64 v[2:3], 11, v[2:3]
	v_lshl_add_u64 v[78:79], v[72:73], 0, v[2:3]
	v_or_b32_e32 v2, s0, v96
	s_lshl_b32 s0, s5, 7
	s_lshl_b32 s30, s52, 10
	v_ashrrev_i32_e32 v3, 31, v2
	s_sub_i32 s0, s0, s30
	v_lshlrev_b64 v[2:3], 11, v[2:3]
	v_bitop3_b32 v4, v17, 7, v188 bitop3:0x48
	s_addk_i32 s0, 0x1000
	v_lshl_or_b32 v2, v4, 4, v2
	s_lshl_b64 s[30:31], s[0:1], 11
	v_lshl_add_u64 v[80:81], s[6:7], 0, v[2:3]
	v_lshl_add_u64 v[2:3], s[30:31], 0, v[10:11]
	v_bitop3_b32 v4, v18, 7, v188 bitop3:0x48
	v_lshl_or_b32 v2, v4, 4, v2
	v_or_b32_e32 v68, s53, v94
	v_lshl_add_u64 v[82:83], s[8:9], 0, v[2:3]
	v_lshlrev_b64 v[2:3], 11, v[68:69]
	v_lshl_add_u64 v[2:3], s[30:31], 0, v[2:3]
	v_bitop3_b32 v4, v19, 7, v188 bitop3:0x48
	v_lshl_or_b32 v2, v4, 4, v2
	v_lshl_add_u64 v[84:85], s[8:9], 0, v[2:3]
	v_mov_b32_e32 v2, 0
	s_mov_b32 s0, 0
	s_mov_b64 s[30:31], 0
	v_mov_b32_e32 v3, v2
	v_mov_b32_e32 v4, v2
	v_mov_b32_e32 v5, v2
	v_mov_b32_e32 v6, v2
	v_mov_b32_e32 v7, v2
	v_mov_b32_e32 v8, v2
	v_mov_b32_e32 v9, v2
	v_mov_b32_e32 v10, v2
	v_mov_b32_e32 v11, v2
	v_mov_b32_e32 v12, v2
	v_mov_b32_e32 v13, v2
	v_mov_b32_e32 v14, v2
	v_mov_b32_e32 v15, v2
	v_mov_b32_e32 v16, v2
	v_mov_b32_e32 v17, v2
	v_mov_b32_e32 v18, v2
	v_mov_b32_e32 v19, v2
	v_mov_b32_e32 v20, v2
	v_mov_b32_e32 v21, v2
	v_mov_b32_e32 v22, v2
	v_mov_b32_e32 v23, v2
	v_mov_b32_e32 v24, v2
	v_mov_b32_e32 v25, v2
	v_mov_b32_e32 v26, v2
	v_mov_b32_e32 v27, v2
	v_mov_b32_e32 v28, v2
	v_mov_b32_e32 v29, v2
	v_mov_b32_e32 v30, v2
	v_mov_b32_e32 v31, v2
	v_mov_b32_e32 v32, v2
	v_mov_b32_e32 v33, v2
	v_mov_b32_e32 v34, v2
	v_mov_b32_e32 v35, v2
	v_mov_b32_e32 v36, v2
	v_mov_b32_e32 v37, v2
	v_mov_b32_e32 v38, v2
	v_mov_b32_e32 v39, v2
	v_mov_b32_e32 v40, v2
	v_mov_b32_e32 v41, v2
	v_mov_b32_e32 v42, v2
	v_mov_b32_e32 v43, v2
	v_mov_b32_e32 v44, v2
	v_mov_b32_e32 v45, v2
	v_mov_b32_e32 v46, v2
	v_mov_b32_e32 v47, v2
	v_mov_b32_e32 v48, v2
	v_mov_b32_e32 v49, v2
	v_mov_b32_e32 v50, v2
	v_mov_b32_e32 v51, v2
	v_mov_b32_e32 v52, v2
	v_mov_b32_e32 v53, v2
	v_mov_b32_e32 v54, v2
	v_mov_b32_e32 v55, v2
	v_mov_b32_e32 v56, v2
	v_mov_b32_e32 v57, v2
	v_mov_b32_e32 v58, v2
	v_mov_b32_e32 v59, v2
	v_mov_b32_e32 v60, v2
	v_mov_b32_e32 v61, v2
	v_mov_b32_e32 v62, v2
	v_mov_b32_e32 v63, v2
	v_mov_b32_e32 v64, v2
	v_mov_b32_e32 v65, v2
	v_readlane_b32 s37, v251, 2
	v_readlane_b32 s38, v251, 3
	v_readlane_b32 s39, v251, 4
	v_readlane_b32 s40, v251, 5
	v_readlane_b32 s41, v251, 6
	v_readlane_b32 s42, v251, 7
	v_readlane_b32 s43, v251, 8
	v_readlane_b32 s44, v251, 9
	v_readlane_b32 s45, v251, 10
	v_readlane_b32 s46, v251, 11
	v_readlane_b32 s47, v251, 12

;     ...
;   const int tid = threadIdx.x, lane = tid & 63, w = __builtin_amdgcn_readfirstlane(tid >> 6), wm = w >> 1, wn = w & 1;
; #pragma unroll
;   for (int i = 0; i < TM; i++)
; #pragma unroll
;     for (int j = 0; j < NJ; j++) acc[i][j] = f32x4{0.f, 0.f, 0.f, 0.f};
;   const u16* ga[NIA];
;   const u16* gb[NIB];
; #pragma unroll
;   for (int ii = 0; ii < NIA; ii++) {
;     int r = (w * NIA + ii) * 8 + (lane >> 3), c = (lane & 7) ^ ((r >> 1) & 7);
;     ga[ii] = A + (size_t)(m0 + r) * 1024 + c * 8;
;   }
; #pragma unroll
;   for (int ii = 0; ii < NIB; ii++) {
;     int r = (w * NIB + ii) * 8 + (lane >> 3), c = (lane & 7) ^ ((r >> 1) & 7);
;     gb[ii] = brow(r) + c * 8;
;   }
; template <int TM>
; DI void phase4_tile(const P& p, char* smem, int m0, int nt) {
;     ...
;   {
;     const u16* wbase = WT + (size_t)(C_FQ + nt * 128) * 1024;
;     auto brow = [&](int r) { return wbase + (size_t)r * 1024; };
;     f32x4 acc[TM][4];
;     if (nt < 16) {
;       gemm_main<128, false, true, 4, decltype(brow), TM>(XN, m0, brow, smem, acc);
.LBB0_544:
	s_ashr_i32 s0, s60, 31
	s_lshr_b32 s0, s0, 28
	s_add_i32 s0, s60, s0
	s_ashr_i32 s53, s0, 4
	s_and_b32 s0, s0, -16
	s_sub_i32 s52, s60, s0
	s_lshl_b32 s62, s52, 7
	v_readfirstlane_b32 s0, v1
	s_add_i32 s16, s62, 0x1410
	v_readlane_b32 s36, v251, 1
	s_lshl_b32 s54, s53, 8
	s_lshr_b32 s55, s0, 7
	s_bfe_u32 s61, s0, 0x10006
	s_lshl_b64 s[0:1], s[16:17], 11
	v_readlane_b32 s50, v251, 15
	v_readlane_b32 s51, v251, 16
	s_add_u32 s2, s50, s0
	s_addc_u32 s3, s51, s1
	s_or_b32 s63, s54, 16
	s_cmp_gt_i32 s52, 7
	s_mov_b64 s[0:1], -1
	v_readlane_b32 s37, v251, 2
	v_readlane_b32 s38, v251, 3
	v_readlane_b32 s39, v251, 4
	v_readlane_b32 s40, v251, 5
	v_readlane_b32 s41, v251, 6
	v_readlane_b32 s42, v251, 7
	v_readlane_b32 s43, v251, 8
	v_readlane_b32 s44, v251, 9
	v_readlane_b32 s45, v251, 10
	v_readlane_b32 s46, v251, 11
	v_readlane_b32 s47, v251, 12
	v_readlane_b32 s48, v251, 13
	v_readlane_b32 s49, v251, 14
	s_cbranch_scc0 .LBB0_612
	v_readfirstlane_b32 s0, v1
	s_lshr_b32 s1, s0, 6
	s_lshl_b32 s16, s1, 5
	v_or_b32_e32 v8, s16, v187
	v_or_b32_e32 v4, 8, v8
	v_lshrrev_b32_e32 v16, 1, v4
	v_xor_b32_e32 v6, v16, v1
	v_lshlrev_b32_e32 v6, 4, v6
	v_add_u32_e32 v2, s54, v8
	v_add_u32_e32 v4, s54, v4
	v_and_b32_e32 v70, 0x70, v6
	v_add_u32_e32 v6, s63, v8
	v_or_b32_e32 v8, 24, v8
	v_ashrrev_i32_e32 v5, 31, v4
	v_readlane_b32 s36, v251, 1
	v_lshrrev_b32_e32 v17, 1, v8
	v_add_u32_e32 v8, s54, v8
	v_lshlrev_b64 v[4:5], 11, v[4:5]
	v_readlane_b32 s48, v251, 13
	v_readlane_b32 s49, v251, 14
	v_xor_b32_e32 v10, v17, v1
	v_ashrrev_i32_e32 v9, 31, v8
	v_lshl_add_u64 v[4:5], s[48:49], 0, v[4:5]
	v_lshlrev_b64 v[8:9], 11, v[8:9]
	v_lshlrev_b32_e32 v10, 4, v10
	v_lshl_add_u64 v[4:5], v[4:5], 0, v[70:71]
	v_lshl_add_u64 v[8:9], s[48:49], 0, v[8:9]
	v_and_b32_e32 v70, 0x70, v10
	s_lshl_b32 s64, s1, 4
	v_ashrrev_i32_e32 v3, 31, v2
	v_lshl_add_u64 v[8:9], v[8:9], 0, v[70:71]
	v_or_b32_e32 v70, s64, v187
	s_lshl_b32 s4, s1, 12
	v_lshlrev_b64 v[2:3], 11, v[2:3]
	v_lshrrev_b32_e32 v18, 1, v70
	s_add_i32 s65, s4, 0
	v_lshl_add_u64 v[2:3], v[72:73], 0, v[2:3]
	v_ashrrev_i32_e32 v7, 31, v6
	v_xor_b32_e32 v14, v18, v1
	v_lshlrev_b64 v[10:11], 11, v[70:71]
	v_or_b32_e32 v70, 8, v70
	s_barrier
; template <int N> DI void wait_vmcnt() { asm volatile("s_waitcnt vmcnt(%0)" ::"n"(N) : "memory"); }
;     ...
;   const int tid = threadIdx.x, lane = tid & 63, w = __builtin_amdgcn_readfirstlane(tid >> 6), wm = w >> 1, wn = w & 1;
; #pragma unroll
;   for (int i = 0; i < TM; i++)
; #pragma unroll
;     for (int j = 0; j < NJ; j++) acc[i][j] = f32x4{0.f, 0.f, 0.f, 0.f};
;   const u16* ga[NIA];
;   const u16* gb[NIB];
; #pragma unroll
;   for (int ii = 0; ii < NIA; ii++) {
;     int r = (w * NIA + ii) * 8 + (lane >> 3), c = (lane & 7) ^ ((r >> 1) & 7);
;     ga[ii] = A + (size_t)(m0 + r) * 1024 + c * 8;
;   }
; #pragma unroll
;   for (int ii = 0; ii < NIB; ii++) {
;     int r = (w * NIB + ii) * 8 + (lane >> 3), c = (lane & 7) ^ ((r >> 1) & 7);
;     gb[ii] = brow(r) + c * 8;
;   }
;   auto glds = [&](int kt, int st) {
;     char* da = smem + st * STAGE + w * (NIA * 1024);
;     char* db = smem + st * STAGE + BM * 128 + w * (NIB * 1024);
; #pragma unroll
;     for (int ii = 0; ii < NIA; ii++) __builtin_amdgcn_global_load_lds((const unsigned*)(ga[ii] + kt * 64), (unsigned*)(da + ii * 1024), 16, 0, 0);
; #pragma unroll
;     for (int ii = 0; ii < NIB; ii++) __builtin_amdgcn_global_load_lds((const unsigned*)(gb[ii] + kt * 64), (unsigned*)(db + ii * 1024), 16, 0, 0);
;   };
;   const int l15 = lane & 15, l4 = lane >> 4;
;   const int swz = (l15 >> 1) & 7;
;   __syncthreads();
;   wait_vmcnt<0>();
;   glds(0, 0);
;   if (NST == 3) glds(1, 1);
; template <int TM>
; DI void phase4_tile(const P& p, char* smem, int m0, int nt) {
;     ...
;     } else {
;       gemm_main<128, false, false, 4, decltype(brow), TM>(XN, m0, brow, smem, acc);
	s_nop 0
	s_mov_b32 m0, s65
	v_lshlrev_b64 v[6:7], 11, v[6:7]
	v_lshlrev_b32_e32 v14, 4, v14
	v_lshrrev_b32_e32 v19, 1, v70
	global_load_lds_dwordx4 v[2:3], off
	s_add_i32 m0, s65, 0x400
	v_lshl_add_u64 v[6:7], v[72:73], 0, v[6:7]
	v_lshl_add_u64 v[12:13], s[2:3], 0, v[10:11]
	v_and_b32_e32 v14, 0x70, v14
	v_mov_b32_e32 v15, v71
	v_xor_b32_e32 v20, v19, v1
	s_lshl_b32 s5, s1, 11
	global_load_lds_dwordx4 v[4:5], off
	s_add_i32 m0, s65, 0x800
	v_lshl_add_u64 v[12:13], v[12:13], 0, v[14:15]
	v_lshlrev_b64 v[14:15], 11, v[70:71]
	v_lshlrev_b32_e32 v20, 4, v20
	global_load_lds_dwordx4 v[6:7], off
	s_add_i32 m0, s65, 0xc00
	s_sub_i32 s1, s65, s5
	v_lshl_add_u64 v[14:15], s[2:3], 0, v[14:15]
	v_and_b32_e32 v70, 0x70, v20
	global_load_lds_dwordx4 v[8:9], off
	s_add_i32 m0, s1, 0x8000
	v_lshl_add_u64 v[14:15], v[14:15], 0, v[70:71]
	global_load_lds_dwordx4 v[12:13], off
	s_add_i32 m0, s1, 0x8400
	v_lshl_add_u64 v[2:3], v[2:3], 0, s[30:31]
	global_load_lds_dwordx4 v[14:15], off
	s_add_i32 m0, s65, 0xc000
	s_add_i32 s1, s5, 0
	global_load_lds_dwordx4 v[2:3], off
	v_lshl_add_u64 v[2:3], v[4:5], 0, s[30:31]
	s_add_i32 m0, s65, 0xc400
	s_add_i32 s16, s16, s54
	global_load_lds_dwordx4 v[2:3], off
	v_lshl_add_u64 v[2:3], v[6:7], 0, s[30:31]
	s_add_i32 m0, s65, 0xc800
	v_bitop3_b32 v4, v16, 7, v1 bitop3:0x48
	global_load_lds_dwordx4 v[2:3], off
	v_lshl_add_u64 v[2:3], v[8:9], 0, s[30:31]
	s_add_i32 m0, s65, 0xcc00
	v_or_b32_e32 v70, s64, v118
	global_load_lds_dwordx4 v[2:3], off
	s_add_i32 m0, s1, 0x14000
	v_lshl_add_u64 v[2:3], v[12:13], 0, s[30:31]
	global_load_lds_dwordx4 v[2:3], off
	v_lshl_add_u64 v[2:3], v[14:15], 0, s[30:31]
	s_add_i32 m0, s1, 0x14400
	s_lshr_b32 s1, s0, 1
	global_load_lds_dwordx4 v[2:3], off
	s_and_b32 s1, s1, 0x1ffffc0
	v_or_b32_e32 v2, s1, v195
	v_and_or_b32 v3, s0, 64, v195
	s_waitcnt vmcnt(12)
	v_lshlrev_b32_e32 v89, 7, v2
	v_add_u32_e32 v2, s16, v187
	v_lshlrev_b32_e32 v88, 7, v3
	v_ashrrev_i32_e32 v3, 31, v2
	v_lshlrev_b64 v[2:3], 11, v[2:3]
	v_lshl_add_u64 v[76:77], v[74:75], 0, v[2:3]
	v_add_u32_e32 v2, s16, v118
	v_ashrrev_i32_e32 v3, 31, v2
	v_lshlrev_b64 v[2:3], 11, v[2:3]
	v_lshl_or_b32 v2, v4, 4, v2
	v_lshl_add_u64 v[78:79], s[18:19], 0, v[2:3]
	v_add_u32_e32 v2, s16, v119
	v_ashrrev_i32_e32 v3, 31, v2
	v_lshlrev_b64 v[2:3], 11, v[2:3]
	v_lshl_add_u64 v[80:81], v[74:75], 0, v[2:3]
	v_add_u32_e32 v2, s16, v120
	s_lshl_b32 s0, s60, 7
	s_lshl_b32 s1, s53, 11
	v_ashrrev_i32_e32 v3, 31, v2
	s_sub_i32 s0, s0, s1
	v_lshlrev_b64 v[2:3], 11, v[2:3]
	v_bitop3_b32 v4, v17, 7, v1 bitop3:0x48
	s_add_i32 s16, s0, 0x1400
	v_lshl_or_b32 v2, v4, 4, v2
	s_lshl_b64 s[0:1], s[16:17], 11
	v_lshl_add_u64 v[82:83], s[18:19], 0, v[2:3]
	v_lshl_add_u64 v[2:3], s[0:1], 0, v[10:11]
	v_bitop3_b32 v4, v18, 7, v1 bitop3:0x48
	v_lshl_or_b32 v2, v4, 4, v2
	v_lshl_add_u64 v[84:85], s[28:29], 0, v[2:3]
	v_lshlrev_b64 v[2:3], 11, v[70:71]
	v_lshl_add_u64 v[2:3], s[0:1], 0, v[2:3]
	v_bitop3_b32 v4, v19, 7, v1 bitop3:0x48
	v_lshl_or_b32 v2, v4, 4, v2
	v_lshl_add_u64 v[86:87], s[28:29], 0, v[2:3]
	v_mov_b32_e32 v2, 0
	s_mov_b32 s16, 0
	s_mov_b64 s[0:1], 0
	v_mov_b32_e32 v3, v2
	v_mov_b32_e32 v4, v2
	v_mov_b32_e32 v5, v2
	v_mov_b32_e32 v6, v2
	v_mov_b32_e32 v7, v2
	v_mov_b32_e32 v8, v2
	v_mov_b32_e32 v9, v2
	v_mov_b32_e32 v10, v2
	v_mov_b32_e32 v11, v2
	v_mov_b32_e32 v12, v2
	v_mov_b32_e32 v13, v2
	v_mov_b32_e32 v14, v2
	v_mov_b32_e32 v15, v2
	v_mov_b32_e32 v16, v2
	v_mov_b32_e32 v17, v2
	v_mov_b32_e32 v18, v2
	v_mov_b32_e32 v19, v2
	v_mov_b32_e32 v20, v2
	v_mov_b32_e32 v21, v2
	v_mov_b32_e32 v22, v2
	v_mov_b32_e32 v23, v2
	v_mov_b32_e32 v24, v2
	v_mov_b32_e32 v25, v2
	v_mov_b32_e32 v26, v2
	v_mov_b32_e32 v27, v2
	v_mov_b32_e32 v28, v2
	v_mov_b32_e32 v29, v2
	v_mov_b32_e32 v30, v2
	v_mov_b32_e32 v31, v2
	v_mov_b32_e32 v32, v2
	v_mov_b32_e32 v33, v2
	v_mov_b32_e32 v34, v2
	v_mov_b32_e32 v35, v2
	v_mov_b32_e32 v36, v2
	v_mov_b32_e32 v37, v2
	v_mov_b32_e32 v38, v2
	v_mov_b32_e32 v39, v2
	v_mov_b32_e32 v40, v2
	v_mov_b32_e32 v41, v2
	v_mov_b32_e32 v42, v2
	v_mov_b32_e32 v43, v2
	v_mov_b32_e32 v44, v2
	v_mov_b32_e32 v45, v2
	v_mov_b32_e32 v46, v2
	v_mov_b32_e32 v47, v2
	v_mov_b32_e32 v48, v2
	v_mov_b32_e32 v49, v2
	v_mov_b32_e32 v50, v2
	v_mov_b32_e32 v51, v2
	v_mov_b32_e32 v52, v2
	v_mov_b32_e32 v53, v2
	v_mov_b32_e32 v54, v2
	v_mov_b32_e32 v55, v2
	v_mov_b32_e32 v56, v2
	v_mov_b32_e32 v57, v2
	v_mov_b32_e32 v58, v2
	v_mov_b32_e32 v59, v2
	v_mov_b32_e32 v60, v2
	v_mov_b32_e32 v61, v2
	v_mov_b32_e32 v62, v2
	v_mov_b32_e32 v63, v2
	v_mov_b32_e32 v64, v2
	v_mov_b32_e32 v65, v2
	v_readlane_b32 s37, v251, 2
	v_readlane_b32 s38, v251, 3
	v_readlane_b32 s39, v251, 4
	v_readlane_b32 s40, v251, 5
	v_readlane_b32 s41, v251, 6
	v_readlane_b32 s42, v251, 7
	v_readlane_b32 s43, v251, 8
	v_readlane_b32 s44, v251, 9
	v_readlane_b32 s45, v251, 10
	v_readlane_b32 s46, v251, 11
	v_readlane_b32 s47, v251, 12
	v_readlane_b32 s50, v251, 15
	v_readlane_b32 s51, v251, 16

; template <int N> DI void wait_vmcnt() { asm volatile("s_waitcnt vmcnt(%0)" ::"n"(N) : "memory"); }
;     ...
;   const int tid = threadIdx.x, lane = tid & 63, w = __builtin_amdgcn_readfirstlane(tid >> 6), wm = w >> 1, wn = w & 1;
; #pragma unroll
;   for (int i = 0; i < TM; i++)
; #pragma unroll
;     for (int j = 0; j < NJ; j++) acc[i][j] = f32x4{0.f, 0.f, 0.f, 0.f};
;   const u16* ga[NIA];
;   const u16* gb[NIB];
; #pragma unroll
;   for (int ii = 0; ii < NIA; ii++) {
;     int r = (w * NIA + ii) * 8 + (lane >> 3), c = (lane & 7) ^ ((r >> 1) & 7);
;     ga[ii] = A + (size_t)(m0 + r) * 1024 + c * 8;
;   }
; #pragma unroll
;   for (int ii = 0; ii < NIB; ii++) {
;     int r = (w * NIB + ii) * 8 + (lane >> 3), c = (lane & 7) ^ ((r >> 1) & 7);
;     gb[ii] = brow(r) + c * 8;
;   }
;   auto glds = [&](int kt, int st) {
;     char* da = smem + st * STAGE + w * (NIA * 1024);
;     char* db = smem + st * STAGE + BM * 128 + w * (NIB * 1024);
; #pragma unroll
;     for (int ii = 0; ii < NIA; ii++) __builtin_amdgcn_global_load_lds((const unsigned*)(ga[ii] + kt * 64), (unsigned*)(da + ii * 1024), 16, 0, 0);
; #pragma unroll
;     for (int ii = 0; ii < NIB; ii++) __builtin_amdgcn_global_load_lds((const unsigned*)(gb[ii] + kt * 64), (unsigned*)(db + ii * 1024), 16, 0, 0);
;   };
;   const int l15 = lane & 15, l4 = lane >> 4;
;   const int swz = (l15 >> 1) & 7;
;   __syncthreads();
;   wait_vmcnt<0>();
;   glds(0, 0);
;   if (NST == 3) glds(1, 1);
; template <int TM>
; DI void phase4_tile(const P& p, char* smem, int m0, int nt) {
;     ...
;     if (nt < 16) {
;       gemm_main<128, false, true, 4, decltype(brow), TM>(XN, m0, brow, smem, acc);
.LBB0_612:
	s_and_b64 vcc, exec, s[0:1]
	s_cbranch_vccz .LBB0_543
	v_readfirstlane_b32 s0, v1
	s_lshr_b32 s1, s0, 6
	s_lshl_b32 s4, s1, 5
	v_or_b32_e32 v8, s4, v187
	v_or_b32_e32 v4, 8, v8
	v_lshrrev_b32_e32 v16, 1, v4
	v_xor_b32_e32 v6, v16, v1
	v_lshlrev_b32_e32 v6, 4, v6
	v_add_u32_e32 v2, s54, v8
	v_add_u32_e32 v4, s54, v4
	v_and_b32_e32 v70, 0x70, v6
	v_add_u32_e32 v6, s63, v8
	v_or_b32_e32 v8, 24, v8
	v_ashrrev_i32_e32 v5, 31, v4
	v_readlane_b32 s36, v251, 1
	v_lshrrev_b32_e32 v17, 1, v8
	v_add_u32_e32 v8, s54, v8
	v_lshlrev_b64 v[4:5], 11, v[4:5]
	v_readlane_b32 s48, v251, 13
	v_readlane_b32 s49, v251, 14
	v_xor_b32_e32 v10, v17, v1
	v_ashrrev_i32_e32 v9, 31, v8
	v_lshl_add_u64 v[4:5], s[48:49], 0, v[4:5]
	v_lshlrev_b64 v[8:9], 11, v[8:9]
	v_lshlrev_b32_e32 v10, 4, v10
	v_lshl_add_u64 v[4:5], v[4:5], 0, v[70:71]
	v_lshl_add_u64 v[8:9], s[48:49], 0, v[8:9]
	v_and_b32_e32 v70, 0x70, v10
	s_lshl_b32 s5, s1, 4
	v_lshl_add_u64 v[8:9], v[8:9], 0, v[70:71]
	v_or_b32_e32 v70, s5, v187
	v_lshrrev_b32_e32 v18, 1, v70
	v_xor_b32_e32 v14, v18, v1
	v_lshlrev_b64 v[10:11], 11, v[70:71]
	v_lshlrev_b32_e32 v14, 4, v14
	v_lshl_add_u64 v[12:13], s[2:3], 0, v[10:11]
	v_and_b32_e32 v14, 0x70, v14
	v_mov_b32_e32 v15, v71
	v_or_b32_e32 v70, 8, v70
	v_lshl_add_u64 v[12:13], v[12:13], 0, v[14:15]
	v_lshlrev_b64 v[14:15], 11, v[70:71]
	v_ashrrev_i32_e32 v3, 31, v2
	v_lshl_add_u64 v[14:15], s[2:3], 0, v[14:15]
	s_lshl_b32 s2, s1, 12
	v_lshlrev_b64 v[2:3], 11, v[2:3]
	s_add_i32 s16, s2, 0
	v_lshl_add_u64 v[2:3], v[72:73], 0, v[2:3]
	v_ashrrev_i32_e32 v7, 31, v6
	s_waitcnt vmcnt(63) expcnt(7) lgkmcnt(15)
	s_barrier
	s_nop 0
	s_mov_b32 m0, s16
	v_lshlrev_b64 v[6:7], 11, v[6:7]
	v_lshrrev_b32_e32 v19, 1, v70
	global_load_lds_dwordx4 v[2:3], off
	s_add_i32 m0, s16, 0x400
	v_lshl_add_u64 v[6:7], v[72:73], 0, v[6:7]
	v_xor_b32_e32 v20, v19, v1
	s_lshl_b32 s3, s1, 11
	global_load_lds_dwordx4 v[4:5], off
	s_add_i32 m0, s16, 0x800
	v_lshlrev_b32_e32 v20, 4, v20
	global_load_lds_dwordx4 v[6:7], off
	s_add_i32 m0, s16, 0xc00
	s_sub_i32 s1, s16, s3
	v_and_b32_e32 v70, 0x70, v20
	global_load_lds_dwordx4 v[8:9], off
	s_add_i32 m0, s1, 0x8000
	v_lshl_add_u64 v[14:15], v[14:15], 0, v[70:71]
	global_load_lds_dwordx4 v[12:13], off
	s_add_i32 m0, s1, 0x8400
	v_lshl_add_u64 v[2:3], v[2:3], 0, s[30:31]
	global_load_lds_dwordx4 v[14:15], off
	s_add_i32 m0, s16, 0xc000
	s_add_i32 s1, s3, 0
	global_load_lds_dwordx4 v[2:3], off
	v_lshl_add_u64 v[2:3], v[4:5], 0, s[30:31]
	s_add_i32 m0, s16, 0xc400
	s_add_i32 s4, s4, s54
	global_load_lds_dwordx4 v[2:3], off
	v_lshl_add_u64 v[2:3], v[6:7], 0, s[30:31]
	s_add_i32 m0, s16, 0xc800
	v_bitop3_b32 v4, v16, 7, v1 bitop3:0x48
	global_load_lds_dwordx4 v[2:3], off
	v_lshl_add_u64 v[2:3], v[8:9], 0, s[30:31]
	s_add_i32 m0, s16, 0xcc00
	v_or_b32_e32 v70, s5, v118
	global_load_lds_dwordx4 v[2:3], off
	s_add_i32 m0, s1, 0x14000
	v_lshl_add_u64 v[2:3], v[12:13], 0, s[30:31]
	global_load_lds_dwordx4 v[2:3], off
	v_lshl_add_u64 v[2:3], v[14:15], 0, s[30:31]
	s_add_i32 m0, s1, 0x14400
	s_lshr_b32 s1, s0, 1
	global_load_lds_dwordx4 v[2:3], off
	s_and_b32 s1, s1, 0x1ffffc0
	v_or_b32_e32 v2, s1, v195
	v_and_or_b32 v3, s0, 64, v195
	s_waitcnt vmcnt(12)
	v_lshlrev_b32_e32 v89, 7, v2
	v_add_u32_e32 v2, s4, v187
	v_lshlrev_b32_e32 v88, 7, v3
	v_ashrrev_i32_e32 v3, 31, v2
	v_lshlrev_b64 v[2:3], 11, v[2:3]
	v_lshl_add_u64 v[76:77], v[74:75], 0, v[2:3]
	v_add_u32_e32 v2, s4, v118
	v_ashrrev_i32_e32 v3, 31, v2
	v_lshlrev_b64 v[2:3], 11, v[2:3]
	v_lshl_or_b32 v2, v4, 4, v2
	v_lshl_add_u64 v[78:79], s[18:19], 0, v[2:3]
	v_add_u32_e32 v2, s4, v119
	v_ashrrev_i32_e32 v3, 31, v2
	v_lshlrev_b64 v[2:3], 11, v[2:3]
	v_lshl_add_u64 v[80:81], v[74:75], 0, v[2:3]
	v_add_u32_e32 v2, s4, v120
	s_lshl_b32 s0, s60, 7
	s_lshl_b32 s1, s53, 11
	v_ashrrev_i32_e32 v3, 31, v2
	s_sub_i32 s0, s0, s1
	v_lshlrev_b64 v[2:3], 11, v[2:3]
	v_bitop3_b32 v4, v17, 7, v1 bitop3:0x48
	s_add_i32 s16, s0, 0x1400
	v_lshl_or_b32 v2, v4, 4, v2
	s_lshl_b64 s[0:1], s[16:17], 11
	v_lshl_add_u64 v[82:83], s[18:19], 0, v[2:3]
	v_lshl_add_u64 v[2:3], s[0:1], 0, v[10:11]
	v_bitop3_b32 v4, v18, 7, v1 bitop3:0x48
	v_lshl_or_b32 v2, v4, 4, v2
	v_lshl_add_u64 v[84:85], s[28:29], 0, v[2:3]
	v_lshlrev_b64 v[2:3], 11, v[70:71]
	v_lshl_add_u64 v[2:3], s[0:1], 0, v[2:3]
	v_bitop3_b32 v4, v19, 7, v1 bitop3:0x48
	v_lshl_or_b32 v2, v4, 4, v2
	v_lshl_add_u64 v[86:87], s[28:29], 0, v[2:3]
	v_mov_b32_e32 v2, 0
	s_mov_b32 s4, 0
	s_mov_b64 s[0:1], 0
	v_mov_b32_e32 v3, v2
	v_mov_b32_e32 v4, v2
	v_mov_b32_e32 v5, v2
	v_mov_b32_e32 v6, v2
	v_mov_b32_e32 v7, v2
	v_mov_b32_e32 v8, v2
	v_mov_b32_e32 v9, v2
	v_mov_b32_e32 v10, v2
	v_mov_b32_e32 v11, v2
	v_mov_b32_e32 v12, v2
	v_mov_b32_e32 v13, v2
	v_mov_b32_e32 v14, v2
	v_mov_b32_e32 v15, v2
	v_mov_b32_e32 v16, v2
	v_mov_b32_e32 v17, v2
	v_mov_b32_e32 v18, v2
	v_mov_b32_e32 v19, v2
	v_mov_b32_e32 v20, v2
	v_mov_b32_e32 v21, v2
	v_mov_b32_e32 v22, v2
	v_mov_b32_e32 v23, v2
	v_mov_b32_e32 v24, v2
	v_mov_b32_e32 v25, v2
	v_mov_b32_e32 v26, v2
	v_mov_b32_e32 v27, v2
	v_mov_b32_e32 v28, v2
	v_mov_b32_e32 v29, v2
	v_mov_b32_e32 v30, v2
	v_mov_b32_e32 v31, v2
	v_mov_b32_e32 v32, v2
	v_mov_b32_e32 v33, v2
	v_mov_b32_e32 v34, v2
	v_mov_b32_e32 v35, v2
	v_mov_b32_e32 v36, v2
	v_mov_b32_e32 v37, v2
	v_mov_b32_e32 v38, v2
	v_mov_b32_e32 v39, v2
	v_mov_b32_e32 v40, v2
	v_mov_b32_e32 v41, v2
	v_mov_b32_e32 v42, v2
	v_mov_b32_e32 v43, v2
	v_mov_b32_e32 v44, v2
	v_mov_b32_e32 v45, v2
	v_mov_b32_e32 v46, v2
	v_mov_b32_e32 v47, v2
	v_mov_b32_e32 v48, v2
	v_mov_b32_e32 v49, v2
	v_mov_b32_e32 v50, v2
	v_mov_b32_e32 v51, v2
	v_mov_b32_e32 v52, v2
	v_mov_b32_e32 v53, v2
	v_mov_b32_e32 v54, v2
	v_mov_b32_e32 v55, v2
	v_mov_b32_e32 v56, v2
	v_mov_b32_e32 v57, v2
	v_mov_b32_e32 v58, v2
	v_mov_b32_e32 v59, v2
	v_mov_b32_e32 v60, v2
	v_mov_b32_e32 v61, v2
	v_mov_b32_e32 v62, v2
	v_mov_b32_e32 v63, v2
	v_mov_b32_e32 v64, v2
	v_mov_b32_e32 v65, v2
	v_readlane_b32 s37, v251, 2
	v_readlane_b32 s38, v251, 3
	v_readlane_b32 s39, v251, 4
	v_readlane_b32 s40, v251, 5
	v_readlane_b32 s41, v251, 6
	v_readlane_b32 s42, v251, 7
	v_readlane_b32 s43, v251, 8
	v_readlane_b32 s44, v251, 9
	v_readlane_b32 s45, v251, 10
	v_readlane_b32 s46, v251, 11
	v_readlane_b32 s47, v251, 12
	v_readlane_b32 s50, v251, 15
	v_readlane_b32 s51, v251, 16

; DI void attn_prompt(const P& p, char* smem, int bh, int qb, float lam, float M2) {
;     ...
;   const u16* kbase = Kn + (size_t)(b * SEQ) * 1024 + h * 128;
;   const u16* vbase = Vt + (size_t)(b * 8 + h) * 128 * SEQ;
;   const u16* gsrc[4];
; #pragma unroll
;   for (int ii = 0; ii < 4; ii++) {
;     int r = (w * 4 + ii) * 8 + (lane >> 3), pos = lane & 7, c = pos ^ ((r >> 1) & 7);
;     if (w < 4) { int key = r & 63, m = r >> 6; gsrc[ii] = kbase + (size_t)key * 1024 + m * 64 + c * 8; }
;     else { int dv = r - 128; gsrc[ii] = vbase + (size_t)dv * SEQ + c * 8; }
;   }
;   const size_t gstep = w < 4 ? (size_t)64 * 1024 : (size_t)64;
;   auto glds = [&](int kt, int bufi) {
;     char* dst = smem + bufi * TILEB + w * 4096;
; #pragma unroll
;     for (int ii = 0; ii < 4; ii++)
;       __builtin_amdgcn_global_load_lds((const unsigned*)(gsrc[ii] + (size_t)kt * gstep), (unsigned*)(dst + ii * 1024), 16, 0, 0);
;   };
;   const int swz16 = ((l31 >> 1) & 7) << 4;
;   const int krow = (map * 64 + l31) * 128, vrow = (128 + l31) * 128;
;   __syncthreads();
;   asm volatile("s_waitcnt vmcnt(0)" ::: "memory");
;   glds(0, 0);
;   glds(1, 1);
.LBB0_770:
	s_lshl_b32 s1, s51, 12
	v_mov_b32_e32 v141, v3
	s_add_i32 s30, s1, 0
	v_mov_b32_e32 v143, v3
	v_lshl_add_u64 v[156:157], v[4:5], 0, v[140:141]
	s_barrier
	s_nop 0
	s_mov_b32 m0, s30
	v_lshl_add_u64 v[154:155], v[6:7], 0, v[142:143]
	global_load_lds_dwordx4 v[156:157], off
	s_add_i32 m0, s30, 0x400
	v_lshl_add_u64 v[152:153], v[10:11], 0, v[140:141]
	v_mov_b32_e32 v145, v3
	global_load_lds_dwordx4 v[154:155], off
	s_add_i32 m0, s30, 0x800
	v_lshl_add_u64 v[158:159], v[8:9], 0, v[144:145]
	global_load_lds_dwordx4 v[152:153], off
	s_add_i32 m0, s30, 0xc00
	s_lshl_b32 s28, s28, 1
	s_mov_b32 s29, s5
	global_load_lds_dwordx4 v[158:159], off
	s_add_i32 m0, s30, 0x8000
	v_lshl_add_u64 v[4:5], v[156:157], 0, s[28:29]
	global_load_lds_dwordx4 v[4:5], off
	v_lshl_add_u64 v[4:5], v[154:155], 0, s[28:29]
	s_add_i32 m0, s30, 0x8400
	s_lshl_b32 s34, s49, 1
	global_load_lds_dwordx4 v[4:5], off
	v_lshl_add_u64 v[4:5], v[152:153], 0, s[28:29]
	s_add_i32 m0, s30, 0x8800
	v_mov_b32_e32 v16, v3
	global_load_lds_dwordx4 v[4:5], off
	v_lshl_add_u64 v[4:5], v[158:159], 0, s[28:29]
	s_add_i32 m0, s30, 0x8c00
	s_lshl_b64 s[52:53], s[28:29], 1
	global_load_lds_dwordx4 v[4:5], off
	v_lshl_add_u64 v[4:5], v[156:157], 0, s[52:53]
	s_add_i32 m0, s30, 0x10000
	s_nop 0
	global_load_lds_dwordx4 v[4:5], off
	v_lshl_add_u64 v[4:5], v[154:155], 0, s[52:53]
	s_add_i32 m0, s30, 0x10400
	s_nop 0
	global_load_lds_dwordx4 v[4:5], off
	v_lshl_add_u64 v[4:5], v[152:153], 0, s[52:53]
	s_add_i32 m0, s30, 0x10800
	s_nop 0
	global_load_lds_dwordx4 v[4:5], off
	v_lshl_add_u64 v[4:5], v[158:159], 0, s[52:53]
	s_add_i32 m0, s30, 0x10c00
	s_lshr_b32 s28, s50, 8
	global_load_lds_dwordx4 v[4:5], off
	v_mov_b32_e32 v17, v3
	s_add_i32 s31, s28, s34
	s_lshl_b32 s30, s48, 13
	v_mov_b32_e32 v2, v3
	v_mov_b32_e32 v4, v3
	v_mov_b32_e32 v5, v3
	v_mov_b32_e32 v6, v3
	v_mov_b32_e32 v7, v3
	v_mov_b32_e32 v8, v3
	v_mov_b32_e32 v9, v3
	v_mov_b32_e32 v10, v3
	v_mov_b32_e32 v11, v3
	v_mov_b32_e32 v12, v3
	v_mov_b32_e32 v13, v3
	v_mov_b32_e32 v14, v3
	v_mov_b32_e32 v15, v3
	v_mov_b64_e32 v[32:33], v[16:17]
	v_mov_b64_e32 v[48:49], v[16:17]
	v_mov_b64_e32 v[64:65], v[16:17]
	v_mov_b64_e32 v[80:81], v[16:17]
	s_add_i32 s31, s31, 1
	s_or_b32 s35, s34, 1
	s_mov_b32 s49, 0
	v_or_b32_e32 v139, s30, v184
	v_or_b32_e32 v141, s30, v185
	v_or_b32_e32 v143, s30, v188
	v_or_b32_e32 v145, s30, v189
	v_mov_b32_e32 v147, 0
	s_mov_b64 s[28:29], 0
	s_mov_b32 s50, 2
	v_mov_b64_e32 v[30:31], v[14:15]
	v_mov_b64_e32 v[28:29], v[12:13]
	v_mov_b64_e32 v[26:27], v[10:11]
	v_mov_b64_e32 v[24:25], v[8:9]
	v_mov_b64_e32 v[22:23], v[6:7]
	v_mov_b64_e32 v[20:21], v[4:5]
	v_mov_b64_e32 v[18:19], v[2:3]
	v_mov_b64_e32 v[46:47], v[14:15]
	v_mov_b64_e32 v[44:45], v[12:13]
	v_mov_b64_e32 v[42:43], v[10:11]
	v_mov_b64_e32 v[40:41], v[8:9]
	v_mov_b64_e32 v[38:39], v[6:7]
	v_mov_b64_e32 v[36:37], v[4:5]
	v_mov_b64_e32 v[34:35], v[2:3]
	v_mov_b64_e32 v[62:63], v[14:15]
	v_mov_b64_e32 v[60:61], v[12:13]
	v_mov_b64_e32 v[58:59], v[10:11]
	v_mov_b64_e32 v[56:57], v[8:9]
	v_mov_b64_e32 v[54:55], v[6:7]
	v_mov_b64_e32 v[52:53], v[4:5]
	v_mov_b64_e32 v[50:51], v[2:3]
	v_mov_b64_e32 v[78:79], v[14:15]
	v_mov_b64_e32 v[76:77], v[12:13]
	v_mov_b64_e32 v[74:75], v[10:11]
	v_mov_b64_e32 v[72:73], v[8:9]
	v_mov_b64_e32 v[70:71], v[6:7]
	v_mov_b64_e32 v[68:69], v[4:5]
	v_mov_b64_e32 v[66:67], v[2:3]
	s_branch .LBB0_772

;     ...
;   const int tid = threadIdx.x, lane = tid & 63, w = __builtin_amdgcn_readfirstlane(tid >> 6), wm = w >> 1, wn = w & 1;
; #pragma unroll
;   for (int i = 0; i < TM; i++)
; #pragma unroll
;     for (int j = 0; j < NJ; j++) acc[i][j] = f32x4{0.f, 0.f, 0.f, 0.f};
;   const u16* ga[NIA];
;   const u16* gb[NIB];
; #pragma unroll
;   for (int ii = 0; ii < NIA; ii++) {
;     int r = (w * NIA + ii) * 8 + (lane >> 3), c = (lane & 7) ^ ((r >> 1) & 7);
;     ga[ii] = A + (size_t)(m0 + r) * 1024 + c * 8;
;   }
; #pragma unroll
;   for (int ii = 0; ii < NIB; ii++) {
;     int r = (w * NIB + ii) * 8 + (lane >> 3), c = (lane & 7) ^ ((r >> 1) & 7);
;     gb[ii] = brow(r) + c * 8;
;   }
; template <int TM>
; DI void phase6_tile(const P& p, char* smem, int m0, int n0) {
;     ...
;     auto brow = [&](int r) {
;       int seg = r >> 6, c = r & 63;
;       int col = (seg == 0 ? C_Z : (seg == 1 ? C_GA : C_GB)) + n0 + c;
;       return WT + (size_t)col * 1024; };
;     gemm_main<192, true, true, 6, decltype(brow), TM>(XN, m0, brow, smem, acc);
.LBB0_804:
	s_ashr_i32 s0, s26, 31
	s_lshr_b32 s0, s0, 28
	s_add_i32 s0, s26, s0
	s_ashr_i32 s1, s0, 4
	s_and_b32 s0, s0, -16
	s_sub_i32 s16, s26, s0
	v_readfirstlane_b32 s0, v136
	s_lshr_b32 s27, s0, 6
	s_lshl_b32 s29, s27, 5
	s_lshl_b32 s3, s1, 8
	v_or_b32_e32 v8, s29, v187
	v_add_u32_e32 v2, s3, v8
	v_ashrrev_i32_e32 v3, 31, v2
	v_lshlrev_b64 v[4:5], 11, v[2:3]
	v_or_b32_e32 v3, 8, v8
	s_mul_i32 s17, s27, 3
	s_lshl_b32 s2, s16, 6
	v_lshrrev_b32_e32 v16, 1, v3
	v_add_u32_e32 v6, s3, v3
	v_or_b32_e32 v8, 24, v8
	s_and_b32 s28, s17, 0xffffff8
	v_xor_b32_e32 v9, v16, v136
	v_ashrrev_i32_e32 v7, 31, v6
	v_readlane_b32 s36, v251, 1
	v_lshrrev_b32_e32 v17, 1, v8
	s_cmp_eq_u32 s28, 8
	v_lshlrev_b64 v[6:7], 11, v[6:7]
	v_readlane_b32 s48, v251, 13
	v_readlane_b32 s49, v251, 14
	v_lshlrev_b32_e32 v3, 4, v9
	v_xor_b32_e32 v10, v17, v136
	s_cselect_b32 s28, s18, 0x2010
	s_add_i32 s31, s17, 1
	v_lshl_add_u64 v[6:7], s[48:49], 0, v[6:7]
	v_and_b32_e32 v110, 0x70, v3
	v_add_u32_e32 v8, s3, v8
	v_lshlrev_b32_e32 v10, 4, v10
	s_mul_i32 s30, s27, 24
	s_and_b32 s33, s31, 0xffffff8
	v_lshl_add_u64 v[6:7], v[6:7], 0, v[110:111]
	v_ashrrev_i32_e32 v9, 31, v8
	v_and_b32_e32 v110, 0x70, v10
	v_or_b32_e32 v10, s30, v187
	s_cmp_eq_u32 s33, 8
	v_lshlrev_b64 v[8:9], 11, v[8:9]
	v_lshrrev_b32_e32 v18, 1, v10
	s_cselect_b32 s33, s18, 0x2010
	s_cmpk_lt_u32 s0, 0xc0
	v_lshl_add_u64 v[8:9], s[48:49], 0, v[8:9]
	v_xor_b32_e32 v12, v18, v136
	s_cselect_b32 s34, 0xc00, s28
	v_and_or_b32 v10, v10, 63, s2
	v_lshl_add_u64 v[8:9], v[8:9], 0, v[110:111]
	v_add_u32_e32 v110, s34, v10
	v_lshlrev_b32_e32 v12, 4, v12
	v_lshlrev_b64 v[10:11], 11, v[110:111]
	v_and_b32_e32 v110, 0x70, v12
	v_lshl_or_b32 v12, s31, 3, v187
	v_readlane_b32 s50, v251, 15
	v_readlane_b32 s51, v251, 16
	v_lshrrev_b32_e32 v19, 1, v12
	v_xor_b32_e32 v14, v19, v136
	v_lshl_add_u64 v[10:11], s[50:51], 0, v[10:11]
	s_cselect_b32 s31, 0xc00, s33
	v_and_or_b32 v12, v12, 63, s2
	v_lshl_add_u64 v[10:11], v[10:11], 0, v[110:111]
	v_add_u32_e32 v110, s31, v12
	v_lshlrev_b32_e32 v14, 4, v14
	s_add_i32 s17, s17, 2
	v_lshlrev_b64 v[12:13], 11, v[110:111]
	v_and_b32_e32 v110, 0x70, v14
	v_lshl_or_b32 v14, s17, 3, v187
	s_and_b32 s17, s17, 0xffffff8
	s_cmp_eq_u32 s17, 8
	s_cselect_b32 s17, s18, 0x2010
	s_cmpk_gt_u32 s0, 0x7f
	s_cselect_b32 s33, s17, 0xc00
	s_lshl_b32 s17, s27, 12
	v_or_b32_e32 v2, 16, v2
	s_add_i32 s35, s17, 0
	v_lshl_add_u64 v[4:5], v[112:113], 0, v[4:5]
	v_ashrrev_i32_e32 v3, 31, v2
	s_barrier
; template <int N> DI void wait_vmcnt() { asm volatile("s_waitcnt vmcnt(%0)" ::"n"(N) : "memory"); }
;     ...
;   const int tid = threadIdx.x, lane = tid & 63, w = __builtin_amdgcn_readfirstlane(tid >> 6), wm = w >> 1, wn = w & 1;
; #pragma unroll
;   for (int i = 0; i < TM; i++)
; #pragma unroll
;     for (int j = 0; j < NJ; j++) acc[i][j] = f32x4{0.f, 0.f, 0.f, 0.f};
;   const u16* ga[NIA];
;   const u16* gb[NIB];
; #pragma unroll
;   for (int ii = 0; ii < NIA; ii++) {
;     int r = (w * NIA + ii) * 8 + (lane >> 3), c = (lane & 7) ^ ((r >> 1) & 7);
;     ga[ii] = A + (size_t)(m0 + r) * 1024 + c * 8;
;   }
; #pragma unroll
;   for (int ii = 0; ii < NIB; ii++) {
;     int r = (w * NIB + ii) * 8 + (lane >> 3), c = (lane & 7) ^ ((r >> 1) & 7);
;     gb[ii] = brow(r) + c * 8;
;   }
;   auto glds = [&](int kt, int st) {
;     char* da = smem + st * STAGE + w * (NIA * 1024);
;     char* db = smem + st * STAGE + BM * 128 + w * (NIB * 1024);
; #pragma unroll
;     for (int ii = 0; ii < NIA; ii++) __builtin_amdgcn_global_load_lds((const unsigned*)(ga[ii] + kt * 64), (unsigned*)(da + ii * 1024), 16, 0, 0);
; #pragma unroll
;     for (int ii = 0; ii < NIB; ii++) __builtin_amdgcn_global_load_lds((const unsigned*)(gb[ii] + kt * 64), (unsigned*)(db + ii * 1024), 16, 0, 0);
;   };
;   const int l15 = lane & 15, l4 = lane >> 4;
;   const int swz = (l15 >> 1) & 7;
;   __syncthreads();
;   wait_vmcnt<0>();
;   glds(0, 0);
;   if (NST == 3) glds(1, 1);
; DI void phase6(const P& p, char* smem, int bid, int nb) {
;   for (int t = bid; t < 128 * 16; t += nb) phase6_tile<4>(p, smem, (t / 16) * 256, (t % 16) * 64);
	s_nop 0
	s_mov_b32 m0, s35
	v_lshlrev_b64 v[2:3], 11, v[2:3]
	global_load_lds_dwordx4 v[4:5], off
	s_add_i32 m0, s35, 0x400
	v_lshl_add_u64 v[2:3], v[112:113], 0, v[2:3]
	v_lshl_add_u64 v[12:13], s[50:51], 0, v[12:13]
	v_lshrrev_b32_e32 v20, 1, v14
	v_and_or_b32 v14, v14, 63, s2
	s_mul_i32 s28, s27, 0xc00
	global_load_lds_dwordx4 v[6:7], off
	s_add_i32 m0, s35, 0x800
	s_lshl_b32 s27, s27, 10
	v_lshl_add_u64 v[12:13], v[12:13], 0, v[110:111]
	v_xor_b32_e32 v21, v20, v136
	v_add_u32_e32 v110, s33, v14
	global_load_lds_dwordx4 v[2:3], off
	s_add_i32 m0, s35, 0xc00
	s_sub_i32 s27, s35, s27
	v_lshlrev_b64 v[14:15], 11, v[110:111]
	v_lshlrev_b32_e32 v21, 4, v21
	global_load_lds_dwordx4 v[8:9], off
	s_add_i32 m0, s27, 0x8000
	v_lshl_add_u64 v[14:15], s[50:51], 0, v[14:15]
	v_and_b32_e32 v110, 0x70, v21
	global_load_lds_dwordx4 v[10:11], off
	s_add_i32 m0, s27, 0x8400
	v_lshl_add_u64 v[14:15], v[14:15], 0, v[110:111]
	global_load_lds_dwordx4 v[12:13], off
	s_add_i32 m0, s27, 0x8800
	s_lshr_b32 s27, s0, 1
	global_load_lds_dwordx4 v[14:15], off
	s_and_b32 s0, s27, 0x1ffffc0
	v_or_b32_e32 v2, s0, v195
	v_and_or_b32 v3, s29, 32, v195
	s_add_i32 s29, s29, s3
	v_lshlrev_b32_e32 v119, 7, v2
	v_or_b32_e32 v2, s29, v187
	v_lshlrev_b32_e32 v118, 7, v3
	v_ashrrev_i32_e32 v3, 31, v2
	v_lshlrev_b64 v[2:3], 11, v[2:3]
	v_lshl_add_u64 v[98:99], v[114:115], 0, v[2:3]
	v_or_b32_e32 v2, s29, v145
	v_ashrrev_i32_e32 v3, 31, v2
	v_lshlrev_b64 v[2:3], 11, v[2:3]
	v_bitop3_b32 v4, v16, 7, v136 bitop3:0x48
	v_lshl_or_b32 v2, v4, 4, v2
	v_lshl_add_u64 v[100:101], s[12:13], 0, v[2:3]
	v_or_b32_e32 v2, s29, v146
	v_ashrrev_i32_e32 v3, 31, v2
	v_lshlrev_b64 v[2:3], 11, v[2:3]
	v_lshl_add_u64 v[102:103], v[114:115], 0, v[2:3]
	v_or_b32_e32 v2, s29, v147
	v_ashrrev_i32_e32 v3, 31, v2
	v_lshlrev_b64 v[2:3], 11, v[2:3]
	v_bitop3_b32 v4, v17, 7, v136 bitop3:0x48
	v_lshl_or_b32 v2, v4, 4, v2
	s_lshl_b32 s0, s26, 6
	v_lshl_add_u64 v[104:105], s[12:13], 0, v[2:3]
	s_add_i32 s34, s34, s0
	v_bitop3_b32 v2, v142, 63, s30 bitop3:0xc8
	v_add_u32_e32 v2, s34, v2
	s_lshl_b32 s1, s1, 10
	v_subrev_u32_e32 v110, s1, v2
	v_lshlrev_b64 v[2:3], 11, v[110:111]
	v_bitop3_b32 v4, v18, 7, v136 bitop3:0x48
	v_lshl_or_b32 v2, v4, 4, v2
	v_lshl_add_u64 v[106:107], s[14:15], 0, v[2:3]
	v_add_u16_e32 v2, s30, v148
	s_add_i32 s31, s31, s0
	v_and_b32_e32 v2, 63, v2
	v_add_u32_e32 v2, s31, v2
	v_subrev_u32_e32 v110, s1, v2
	v_lshlrev_b64 v[2:3], 11, v[110:111]
	v_bitop3_b32 v4, v19, 7, v136 bitop3:0x48
	v_lshl_or_b32 v2, v4, 4, v2
	v_lshl_add_u64 v[108:109], s[14:15], 0, v[2:3]
	v_add_u16_e32 v2, s30, v150
	s_add_i32 s33, s33, s0
	v_and_b32_e32 v2, 63, v2
	v_add_u32_e32 v2, s33, v2
	v_subrev_u32_e32 v110, s1, v2
	v_lshlrev_b64 v[2:3], 11, v[110:111]
	v_bitop3_b32 v4, v20, 7, v136 bitop3:0x48
	v_lshl_or_b32 v2, v4, 4, v2
	v_lshl_add_u64 v[116:117], s[14:15], 0, v[2:3]
	s_mov_b32 s29, 0
	s_mov_b64 s[0:1], 0
	v_mov_b32_e32 v2, 0
	v_mov_b32_e32 v3, v111
	v_mov_b32_e32 v4, v111
	v_mov_b32_e32 v5, v111
	v_mov_b32_e32 v6, 0
	v_mov_b32_e32 v7, v111
	v_mov_b32_e32 v8, v111
	v_mov_b32_e32 v9, v111
	v_mov_b32_e32 v10, 0
	v_mov_b32_e32 v11, v111
	v_mov_b32_e32 v12, v111
	v_mov_b32_e32 v13, v111
	v_mov_b32_e32 v14, 0
	v_mov_b32_e32 v15, v111
	v_mov_b32_e32 v16, v111
	v_mov_b32_e32 v17, v111
	v_mov_b32_e32 v18, 0
	v_mov_b32_e32 v19, v111
	v_mov_b32_e32 v20, v111
	v_mov_b32_e32 v21, v111
	v_mov_b32_e32 v22, 0
	v_mov_b32_e32 v23, v111
	v_mov_b32_e32 v24, v111
	v_mov_b32_e32 v25, v111
	v_mov_b32_e32 v26, 0
	v_mov_b32_e32 v27, v111
	v_mov_b32_e32 v28, v111
	v_mov_b32_e32 v29, v111
	s_waitcnt vmcnt(0)
	v_mov_b32_e32 v30, 0
	v_mov_b32_e32 v31, v111
	v_mov_b32_e32 v32, v111
	v_mov_b32_e32 v33, v111
	v_mov_b32_e32 v34, 0
	v_mov_b32_e32 v35, v111
	v_mov_b32_e32 v36, v111
	v_mov_b32_e32 v37, v111
	v_mov_b32_e32 v38, 0
	v_mov_b32_e32 v39, v111
	v_mov_b32_e32 v40, v111
	v_mov_b32_e32 v41, v111
	v_mov_b32_e32 v42, 0
	v_mov_b32_e32 v43, v111
	v_mov_b32_e32 v44, v111
	v_mov_b32_e32 v45, v111
	v_mov_b32_e32 v46, 0
	v_mov_b32_e32 v47, v111
	v_mov_b32_e32 v48, v111
	v_mov_b32_e32 v49, v111
	v_mov_b32_e32 v50, 0
	v_mov_b32_e32 v51, v111
	v_mov_b32_e32 v52, v111
	v_mov_b32_e32 v53, v111
	v_mov_b32_e32 v54, 0
	v_mov_b32_e32 v55, v111
	v_mov_b32_e32 v56, v111
	v_mov_b32_e32 v57, v111
	v_mov_b32_e32 v58, 0
	v_mov_b32_e32 v59, v111
	v_mov_b32_e32 v60, v111
	v_mov_b32_e32 v61, v111
	v_mov_b32_e32 v62, 0
	v_mov_b32_e32 v63, v111
	v_mov_b32_e32 v64, v111
	v_mov_b32_e32 v65, v111
	v_mov_b32_e32 v66, 0
	v_mov_b32_e32 v67, v111
	v_mov_b32_e32 v68, v111
	v_mov_b32_e32 v69, v111
	v_mov_b32_e32 v70, 0
	v_mov_b32_e32 v71, v111
	v_mov_b32_e32 v72, v111
	v_mov_b32_e32 v73, v111
	v_mov_b32_e32 v74, 0
	v_mov_b32_e32 v75, v111
	v_mov_b32_e32 v76, v111
	v_mov_b32_e32 v77, v111
	v_mov_b32_e32 v78, 0
	v_mov_b32_e32 v79, v111
	v_mov_b32_e32 v80, v111
	v_mov_b32_e32 v81, v111
	v_mov_b32_e32 v82, 0
	v_mov_b32_e32 v83, v111
	v_mov_b32_e32 v84, v111
	v_mov_b32_e32 v85, v111
	v_mov_b32_e32 v86, 0
	v_mov_b32_e32 v87, v111
	v_mov_b32_e32 v88, v111
	v_mov_b32_e32 v89, v111
	v_mov_b32_e32 v90, 0
	v_mov_b32_e32 v91, v111
	v_mov_b32_e32 v92, v111
	v_mov_b32_e32 v93, v111
	v_mov_b32_e32 v94, 0
	v_mov_b32_e32 v95, v111
	v_mov_b32_e32 v96, v111
	v_mov_b32_e32 v97, v111
	v_readlane_b32 s37, v251, 2
	v_readlane_b32 s38, v251, 3
	v_readlane_b32 s39, v251, 4
	v_readlane_b32 s40, v251, 5
	v_readlane_b32 s41, v251, 6
	v_readlane_b32 s42, v251, 7
	v_readlane_b32 s43, v251, 8
	v_readlane_b32 s44, v251, 9
	v_readlane_b32 s45, v251, 10
	v_readlane_b32 s46, v251, 11
	v_readlane_b32 s47, v251, 12

; template <int N> DI void wait_vmcnt() { asm volatile("s_waitcnt vmcnt(%0)" ::"n"(N) : "memory"); }
;     ...
;   const int tid = threadIdx.x, lane = tid & 63, w = __builtin_amdgcn_readfirstlane(tid >> 6), wm = w >> 1, wn = w & 1;
; #pragma unroll
;   for (int i = 0; i < TM; i++)
; #pragma unroll
;     for (int j = 0; j < NJ; j++) acc[i][j] = f32x4{0.f, 0.f, 0.f, 0.f};
;   const u16* ga[NIA];
;   const u16* gb[NIB];
; #pragma unroll
;   for (int ii = 0; ii < NIA; ii++) {
;     int r = (w * NIA + ii) * 8 + (lane >> 3), c = (lane & 7) ^ ((r >> 1) & 7);
;     ga[ii] = A + (size_t)(m0 + r) * 1024 + c * 8;
;   }
; #pragma unroll
;   for (int ii = 0; ii < NIB; ii++) {
;     int r = (w * NIB + ii) * 8 + (lane >> 3), c = (lane & 7) ^ ((r >> 1) & 7);
;     gb[ii] = brow(r) + c * 8;
;   }
;   auto glds = [&](int kt, int st) {
;     char* da = smem + st * STAGE + w * (NIA * 1024);
;     char* db = smem + st * STAGE + BM * 128 + w * (NIB * 1024);
; #pragma unroll
;     for (int ii = 0; ii < NIA; ii++) __builtin_amdgcn_global_load_lds((const unsigned*)(ga[ii] + kt * 64), (unsigned*)(da + ii * 1024), 16, 0, 0);
; #pragma unroll
;     for (int ii = 0; ii < NIB; ii++) __builtin_amdgcn_global_load_lds((const unsigned*)(gb[ii] + kt * 64), (unsigned*)(db + ii * 1024), 16, 0, 0);
;   };
;   const int l15 = lane & 15, l4 = lane >> 4;
;   const int swz = (l15 >> 1) & 7;
;   __syncthreads();
;   wait_vmcnt<0>();
;   glds(0, 0);
;   if (NST == 3) glds(1, 1);
; template <int TM>
; DI void phase7_tile(const P& p, char* smem, int m0, int n0) {
;     ...
;   f32x4 acc[TM][4];
;   auto brow = [&](int r) { return WT + (size_t)(n0 + r) * 1024; };
;   gemm_main<128, false, true, 4, decltype(brow), TM>(MG, m0, brow, smem, acc);
.LBB0_827:
	s_ashr_i32 s12, s15, 31
	s_lshr_b32 s12, s12, 29
	s_add_i32 s12, s15, s12
	s_ashr_i32 s13, s12, 3
	s_and_b32 s12, s12, 0x1fffff8
	s_sub_i32 s12, s15, s12
	s_lshl_b32 s16, s12, 7
	v_readfirstlane_b32 s12, v84
	s_lshr_b32 s19, s12, 6
	s_lshl_b32 s26, s19, 5
	s_lshl_b32 s18, s13, 8
	v_or_b32_e32 v8, s26, v187
	v_add_u32_e32 v2, s18, v8
	v_ashrrev_i32_e32 v3, 31, v2
	v_lshlrev_b64 v[4:5], 11, v[2:3]
	v_or_b32_e32 v3, 8, v8
	v_lshrrev_b32_e32 v14, 1, v3
	v_add_u32_e32 v6, s18, v3
	v_or_b32_e32 v8, 24, v8
	v_xor_b32_e32 v9, v14, v84
	v_ashrrev_i32_e32 v7, 31, v6
	v_lshrrev_b32_e32 v15, 1, v8
	s_lshl_b32 s27, s19, 4
	v_lshlrev_b64 v[6:7], 11, v[6:7]
	v_lshlrev_b32_e32 v3, 4, v9
	v_xor_b32_e32 v10, v15, v84
	v_add_u32_e32 v8, s18, v8
	v_or_b32_e32 v12, s27, v187
	s_lshl_b32 s24, s19, 12
	v_lshl_add_u64 v[6:7], s[2:3], 0, v[6:7]
	v_and_b32_e32 v66, 0x70, v3
	v_or_b32_e32 v2, 16, v2
	v_ashrrev_i32_e32 v9, 31, v8
	v_lshlrev_b32_e32 v10, 4, v10
	v_lshrrev_b32_e32 v16, 1, v12
	s_add_i32 s28, s24, 0
	v_lshl_add_u64 v[4:5], v[68:69], 0, v[4:5]
	v_lshl_add_u64 v[6:7], v[6:7], 0, v[66:67]
	v_ashrrev_i32_e32 v3, 31, v2
	v_lshlrev_b64 v[8:9], 11, v[8:9]
	v_and_b32_e32 v66, 0x70, v10
	v_xor_b32_e32 v13, v16, v84
	v_add_u32_e32 v10, s16, v12
	v_or_b32_e32 v12, 8, v12
	s_barrier
	s_nop 0
	s_mov_b32 m0, s28
	v_lshlrev_b64 v[2:3], 11, v[2:3]
	v_lshl_add_u64 v[8:9], s[2:3], 0, v[8:9]
	v_ashrrev_i32_e32 v11, 31, v10
	v_lshlrev_b32_e32 v13, 4, v13
	v_lshrrev_b32_e32 v17, 1, v12
	v_add_u32_e32 v12, s16, v12
	global_load_lds_dwordx4 v[4:5], off
	s_add_i32 m0, s28, 0x400
	v_lshl_add_u64 v[2:3], v[68:69], 0, v[2:3]
	v_lshl_add_u64 v[8:9], v[8:9], 0, v[66:67]
	v_lshlrev_b64 v[10:11], 11, v[10:11]
	v_and_b32_e32 v66, 0x70, v13
	v_xor_b32_e32 v18, v17, v84
	v_ashrrev_i32_e32 v13, 31, v12
	s_lshl_b32 s25, s19, 11
	global_load_lds_dwordx4 v[6:7], off
	s_add_i32 m0, s28, 0x800
	v_lshl_add_u64 v[10:11], s[4:5], 0, v[10:11]
	v_lshlrev_b64 v[12:13], 11, v[12:13]
	v_lshlrev_b32_e32 v18, 4, v18
	global_load_lds_dwordx4 v[2:3], off
	s_add_i32 m0, s28, 0xc00
	s_sub_i32 s19, s28, s25
	v_lshl_add_u64 v[10:11], v[10:11], 0, v[66:67]
	v_lshl_add_u64 v[12:13], s[4:5], 0, v[12:13]
	v_and_b32_e32 v66, 0x70, v18
	global_load_lds_dwordx4 v[8:9], off
	s_add_i32 m0, s19, 0x8000
	v_lshl_add_u64 v[12:13], v[12:13], 0, v[66:67]
	global_load_lds_dwordx4 v[10:11], off
	s_add_i32 m0, s19, 0x8400
	v_lshl_add_u64 v[4:5], v[4:5], 0, s[10:11]
	global_load_lds_dwordx4 v[12:13], off
	s_add_i32 m0, s28, 0xc000
	v_lshl_add_u64 v[2:3], v[2:3], 0, s[10:11]
	global_load_lds_dwordx4 v[4:5], off
	v_lshl_add_u64 v[4:5], v[6:7], 0, s[10:11]
	s_add_i32 m0, s28, 0xc400
	s_add_i32 s19, s25, 0
	global_load_lds_dwordx4 v[4:5], off
	s_add_i32 m0, s28, 0xc800
	s_and_b32 s17, s12, 64
	global_load_lds_dwordx4 v[2:3], off
	v_lshl_add_u64 v[2:3], v[8:9], 0, s[10:11]
	s_add_i32 m0, s28, 0xcc00
	s_add_i32 s26, s26, s18
	global_load_lds_dwordx4 v[2:3], off
	s_add_i32 m0, s19, 0x14000
	v_lshl_add_u64 v[2:3], v[10:11], 0, s[10:11]
	global_load_lds_dwordx4 v[2:3], off
	v_lshl_add_u64 v[2:3], v[12:13], 0, s[10:11]
	s_add_i32 m0, s19, 0x14400
	s_lshr_b32 s19, s12, 1
	global_load_lds_dwordx4 v[2:3], off
	s_and_b32 s12, s19, 0x1ffffc0
	v_or_b32_e32 v2, s12, v195
	v_or_b32_e32 v3, s17, v195
	v_lshlrev_b32_e32 v97, 7, v2
	v_or_b32_e32 v2, s26, v187
	v_lshlrev_b32_e32 v66, 7, v3
	v_ashrrev_i32_e32 v3, 31, v2
	v_lshlrev_b64 v[2:3], 11, v[2:3]
	v_lshl_add_u64 v[72:73], v[70:71], 0, v[2:3]
	v_or_b32_e32 v2, s26, v94
	v_ashrrev_i32_e32 v3, 31, v2
	v_lshlrev_b64 v[2:3], 11, v[2:3]
	v_bitop3_b32 v4, v14, 7, v84 bitop3:0x48
	v_lshl_or_b32 v2, v4, 4, v2
	v_lshl_add_u64 v[74:75], s[6:7], 0, v[2:3]
	v_or_b32_e32 v2, s26, v95
	v_ashrrev_i32_e32 v3, 31, v2
	v_lshlrev_b64 v[2:3], 11, v[2:3]
	v_lshl_add_u64 v[76:77], v[70:71], 0, v[2:3]
	v_or_b32_e32 v2, s26, v96
	v_ashrrev_i32_e32 v3, 31, v2
	v_lshlrev_b64 v[2:3], 11, v[2:3]
	v_bitop3_b32 v4, v15, 7, v84 bitop3:0x48
	s_lshl_b32 s12, s15, 7
	v_lshl_or_b32 v2, v4, 4, v2
	s_add_i32 s27, s27, s12
	v_lshl_add_u64 v[78:79], s[6:7], 0, v[2:3]
	v_or_b32_e32 v2, s27, v187
	s_lshl_b32 s12, s13, 10
	v_subrev_u32_e32 v2, s12, v2
	v_ashrrev_i32_e32 v3, 31, v2
	v_lshlrev_b64 v[2:3], 11, v[2:3]
	v_bitop3_b32 v4, v16, 7, v84 bitop3:0x48
	v_lshl_or_b32 v2, v4, 4, v2
	v_lshl_add_u64 v[80:81], s[8:9], 0, v[2:3]
	v_or_b32_e32 v2, s27, v94
	v_subrev_u32_e32 v2, s12, v2
	v_ashrrev_i32_e32 v3, 31, v2
	v_lshlrev_b64 v[2:3], 11, v[2:3]
	v_bitop3_b32 v4, v17, 7, v84 bitop3:0x48
	v_lshl_or_b32 v2, v4, 4, v2
	v_lshl_add_u64 v[82:83], s[8:9], 0, v[2:3]
	s_mov_b32 s26, 0
	s_mov_b64 s[12:13], 0
	v_mov_b32_e32 v2, 0
	v_mov_b32_e32 v3, v67
	v_mov_b32_e32 v4, v67
	v_mov_b32_e32 v5, v67
	v_mov_b32_e32 v6, 0
	v_mov_b32_e32 v7, v67
	v_mov_b32_e32 v8, v67
	v_mov_b32_e32 v9, v67
	v_mov_b32_e32 v10, 0
	v_mov_b32_e32 v11, v67
	v_mov_b32_e32 v12, v67
	v_mov_b32_e32 v13, v67
	v_mov_b32_e32 v14, 0
	v_mov_b32_e32 v15, v67
	v_mov_b32_e32 v16, v67
	v_mov_b32_e32 v17, v67
	v_mov_b32_e32 v18, 0
	v_mov_b32_e32 v19, v67
	v_mov_b32_e32 v20, v67
	v_mov_b32_e32 v21, v67
	v_mov_b32_e32 v22, 0
	v_mov_b32_e32 v23, v67
	v_mov_b32_e32 v24, v67
	v_mov_b32_e32 v25, v67
	v_mov_b32_e32 v26, 0
	v_mov_b32_e32 v27, v67
	v_mov_b32_e32 v28, v67
	v_mov_b32_e32 v29, v67
	v_mov_b32_e32 v30, 0
	v_mov_b32_e32 v31, v67
	v_mov_b32_e32 v32, v67
	v_mov_b32_e32 v33, v67
	v_mov_b32_e32 v34, 0
	v_mov_b32_e32 v35, v67
	v_mov_b32_e32 v36, v67
	v_mov_b32_e32 v37, v67
	v_mov_b32_e32 v38, 0
	v_mov_b32_e32 v39, v67
	v_mov_b32_e32 v40, v67
	v_mov_b32_e32 v41, v67
	v_mov_b32_e32 v42, 0
	v_mov_b32_e32 v43, v67
	v_mov_b32_e32 v44, v67
	v_mov_b32_e32 v45, v67
	v_mov_b32_e32 v46, 0
	v_mov_b32_e32 v47, v67
	v_mov_b32_e32 v48, v67
	v_mov_b32_e32 v49, v67
	v_mov_b32_e32 v50, 0
	v_mov_b32_e32 v51, v67
	v_mov_b32_e32 v52, v67
	v_mov_b32_e32 v53, v67
	v_mov_b32_e32 v54, 0
	v_mov_b32_e32 v55, v67
	v_mov_b32_e32 v56, v67
	v_mov_b32_e32 v57, v67
	v_mov_b32_e32 v58, 0
	v_mov_b32_e32 v59, v67
	v_mov_b32_e32 v60, v67
	v_mov_b32_e32 v61, v67
	v_mov_b32_e32 v62, 0
	v_mov_b32_e32 v63, v67
	v_mov_b32_e32 v64, v67
	v_mov_b32_e32 v65, v67

; template <int N> DI void wait_vmcnt() { asm volatile("s_waitcnt vmcnt(%0)" ::"n"(N) : "memory"); }
;     ...
;   const int tid = threadIdx.x, lane = tid & 63, w = __builtin_amdgcn_readfirstlane(tid >> 6), wm = w >> 1, wn = w & 1;
; #pragma unroll
;   for (int i = 0; i < TM; i++)
; #pragma unroll
;     for (int j = 0; j < NJ; j++) acc[i][j] = f32x4{0.f, 0.f, 0.f, 0.f};
;   const u16* ga[NIA];
;   const u16* gb[NIB];
; #pragma unroll
;   for (int ii = 0; ii < NIA; ii++) {
;     int r = (w * NIA + ii) * 8 + (lane >> 3), c = (lane & 7) ^ ((r >> 1) & 7);
;     ga[ii] = A + (size_t)(m0 + r) * 1024 + c * 8;
;   }
; #pragma unroll
;   for (int ii = 0; ii < NIB; ii++) {
;     int r = (w * NIB + ii) * 8 + (lane >> 3), c = (lane & 7) ^ ((r >> 1) & 7);
;     gb[ii] = brow(r) + c * 8;
;   }
;   auto glds = [&](int kt, int st) {
;     char* da = smem + st * STAGE + w * (NIA * 1024);
;     char* db = smem + st * STAGE + BM * 128 + w * (NIB * 1024);
; #pragma unroll
;     for (int ii = 0; ii < NIA; ii++) __builtin_amdgcn_global_load_lds((const unsigned*)(ga[ii] + kt * 64), (unsigned*)(da + ii * 1024), 16, 0, 0);
; #pragma unroll
;     for (int ii = 0; ii < NIB; ii++) __builtin_amdgcn_global_load_lds((const unsigned*)(gb[ii] + kt * 64), (unsigned*)(db + ii * 1024), 16, 0, 0);
;   };
;   const int l15 = lane & 15, l4 = lane >> 4;
;   const int swz = (l15 >> 1) & 7;
;   __syncthreads();
;   wait_vmcnt<0>();
;   glds(0, 0);
;   if (NST == 3) glds(1, 1);
; template <int TM>
; DI void phase9_tile(const P& p, char* smem, int m0, int nt) {
;     ...
;   {
;     f32x4 acc[TM][4];
;     auto brow = [&](int r) { return WT + (size_t)(n0 + r) * 1024; };
;     gemm_main<128, false, true, 4, decltype(brow), TM>(HN, m0, brow, smem, acc);
.LBB0_882:
	s_ashr_i32 s2, s22, 31
	s_lshr_b32 s2, s2, 28
	s_add_i32 s2, s22, s2
	s_ashr_i32 s3, s2, 4
	s_and_b32 s2, s2, -16
	v_readfirstlane_b32 s25, v86
	s_sub_i32 s18, s22, s2
	s_lshr_b32 s2, s25, 6
	s_lshl_b32 s28, s2, 5
	s_lshl_b32 s19, s3, 8
	v_or_b32_e32 v8, s28, v187
	v_add_u32_e32 v2, s19, v8
	v_ashrrev_i32_e32 v3, 31, v2
	v_lshlrev_b64 v[4:5], 11, v[2:3]
	v_or_b32_e32 v3, 8, v8
	v_lshrrev_b32_e32 v14, 1, v3
	v_add_u32_e32 v6, s19, v3
	v_or_b32_e32 v8, 24, v8
	v_xor_b32_e32 v9, v14, v86
	v_ashrrev_i32_e32 v7, 31, v6
	v_lshrrev_b32_e32 v15, 1, v8
	s_lshl_b32 s29, s2, 4
	v_lshlrev_b64 v[6:7], 11, v[6:7]
	v_lshlrev_b32_e32 v3, 4, v9
	v_xor_b32_e32 v10, v15, v86
	v_add_u32_e32 v8, s19, v8
	v_or_b32_e32 v12, s29, v187
	s_lshl_b32 s26, s2, 12
	s_lshl_b32 s23, s18, 7
	v_lshl_add_u64 v[6:7], s[6:7], 0, v[6:7]
	v_and_b32_e32 v68, 0x70, v3
	v_or_b32_e32 v2, 16, v2
	v_ashrrev_i32_e32 v9, 31, v8
	v_lshlrev_b32_e32 v10, 4, v10
	v_lshrrev_b32_e32 v16, 1, v12
	s_add_i32 s24, s26, 0
	v_lshl_add_u64 v[4:5], v[70:71], 0, v[4:5]
	v_lshl_add_u64 v[6:7], v[6:7], 0, v[68:69]
	v_ashrrev_i32_e32 v3, 31, v2
	v_lshlrev_b64 v[8:9], 11, v[8:9]
	v_and_b32_e32 v68, 0x70, v10
	v_xor_b32_e32 v13, v16, v86
	v_add_u32_e32 v10, s23, v12
	v_or_b32_e32 v12, 8, v12
	s_barrier
	s_nop 0
	s_mov_b32 m0, s24
	v_lshlrev_b64 v[2:3], 11, v[2:3]
	v_lshl_add_u64 v[8:9], s[6:7], 0, v[8:9]
	v_ashrrev_i32_e32 v11, 31, v10
	v_lshlrev_b32_e32 v13, 4, v13
	v_lshrrev_b32_e32 v17, 1, v12
	v_add_u32_e32 v12, s23, v12
	global_load_lds_dwordx4 v[4:5], off
	s_add_i32 m0, s24, 0x400
	v_lshl_add_u64 v[2:3], v[70:71], 0, v[2:3]
	v_lshl_add_u64 v[8:9], v[8:9], 0, v[68:69]
	v_lshlrev_b64 v[10:11], 11, v[10:11]
	v_and_b32_e32 v68, 0x70, v13
	v_xor_b32_e32 v18, v17, v86
	v_ashrrev_i32_e32 v13, 31, v12
	s_lshl_b32 s27, s2, 11
	global_load_lds_dwordx4 v[6:7], off
	s_add_i32 m0, s24, 0x800
	v_lshl_add_u64 v[10:11], s[8:9], 0, v[10:11]
	v_lshlrev_b64 v[12:13], 11, v[12:13]
	v_lshlrev_b32_e32 v18, 4, v18
	global_load_lds_dwordx4 v[2:3], off
	s_add_i32 m0, s24, 0xc00
	s_sub_i32 s2, s24, s27
	v_lshl_add_u64 v[10:11], v[10:11], 0, v[68:69]
	v_lshl_add_u64 v[12:13], s[8:9], 0, v[12:13]
	v_and_b32_e32 v68, 0x70, v18
	global_load_lds_dwordx4 v[8:9], off
	s_add_i32 m0, s2, 0x8000
	v_lshl_add_u64 v[12:13], v[12:13], 0, v[68:69]
	global_load_lds_dwordx4 v[10:11], off
	s_add_i32 m0, s2, 0x8400
	v_lshl_add_u64 v[4:5], v[4:5], 0, s[16:17]
	global_load_lds_dwordx4 v[12:13], off
	s_add_i32 m0, s24, 0xc000
	v_lshl_add_u64 v[2:3], v[2:3], 0, s[16:17]
	global_load_lds_dwordx4 v[4:5], off
	v_lshl_add_u64 v[4:5], v[6:7], 0, s[16:17]
	s_add_i32 m0, s24, 0xc400
	s_add_i32 s2, s27, 0
	global_load_lds_dwordx4 v[4:5], off
	s_add_i32 m0, s24, 0xc800
	s_add_i32 s28, s28, s19
	global_load_lds_dwordx4 v[2:3], off
	v_lshl_add_u64 v[2:3], v[8:9], 0, s[16:17]
	s_add_i32 m0, s24, 0xcc00
	s_lshr_b32 s24, s25, 1
	global_load_lds_dwordx4 v[2:3], off
	s_add_i32 m0, s2, 0x14000
	v_lshl_add_u64 v[2:3], v[10:11], 0, s[16:17]
	global_load_lds_dwordx4 v[2:3], off
	v_lshl_add_u64 v[2:3], v[12:13], 0, s[16:17]
	s_add_i32 m0, s2, 0x14400
	s_and_b32 s2, s24, 0x1ffffc0
	global_load_lds_dwordx4 v[2:3], off
	v_or_b32_e32 v2, s2, v195
	v_and_or_b32 v3, s25, 64, v195
	v_lshlrev_b32_e32 v115, 7, v2
	v_or_b32_e32 v2, s28, v187
	v_lshlrev_b32_e32 v68, 7, v3
	v_ashrrev_i32_e32 v3, 31, v2
	v_lshlrev_b64 v[2:3], 11, v[2:3]
	v_lshl_add_u64 v[74:75], v[72:73], 0, v[2:3]
	v_or_b32_e32 v2, s28, v111
	v_ashrrev_i32_e32 v3, 31, v2
	v_lshlrev_b64 v[2:3], 11, v[2:3]
	v_bitop3_b32 v4, v14, 7, v86 bitop3:0x48
	v_lshl_or_b32 v2, v4, 4, v2
	v_lshl_add_u64 v[76:77], s[12:13], 0, v[2:3]
	v_or_b32_e32 v2, s28, v112
	v_ashrrev_i32_e32 v3, 31, v2
	v_lshlrev_b64 v[2:3], 11, v[2:3]
	v_lshl_add_u64 v[78:79], v[72:73], 0, v[2:3]
	v_or_b32_e32 v2, s28, v113
	v_ashrrev_i32_e32 v3, 31, v2
	v_lshlrev_b64 v[2:3], 11, v[2:3]
	v_bitop3_b32 v4, v15, 7, v86 bitop3:0x48
	s_lshl_b32 s2, s22, 7
	v_lshl_or_b32 v2, v4, 4, v2
	s_add_i32 s29, s29, s2
	v_lshl_add_u64 v[80:81], s[12:13], 0, v[2:3]
	v_or_b32_e32 v2, s29, v187
	s_lshl_b32 s2, s3, 11
	v_subrev_u32_e32 v2, s2, v2
	v_ashrrev_i32_e32 v3, 31, v2
	v_lshlrev_b64 v[2:3], 11, v[2:3]
	v_bitop3_b32 v4, v16, 7, v86 bitop3:0x48
	v_lshl_or_b32 v2, v4, 4, v2
	v_lshl_add_u64 v[82:83], s[14:15], 0, v[2:3]
	v_or_b32_e32 v2, s29, v111
	v_subrev_u32_e32 v2, s2, v2
	v_ashrrev_i32_e32 v3, 31, v2
	v_lshlrev_b64 v[2:3], 11, v[2:3]
	v_bitop3_b32 v4, v17, 7, v86 bitop3:0x48
	v_lshl_or_b32 v2, v4, 4, v2
	v_lshl_add_u64 v[84:85], s[14:15], 0, v[2:3]
	v_mov_b32_e32 v2, 0
	s_mov_b32 s28, 0
	s_mov_b64 s[2:3], 0
	v_mov_b32_e32 v3, v2
	v_mov_b32_e32 v4, v2
	v_mov_b32_e32 v5, v2
	v_mov_b32_e32 v6, v2
	v_mov_b32_e32 v7, v2
	v_mov_b32_e32 v8, v2
	v_mov_b32_e32 v9, v2
	v_mov_b32_e32 v10, v2
	v_mov_b32_e32 v11, v2
	v_mov_b32_e32 v12, v2
	v_mov_b32_e32 v13, v2
	v_mov_b32_e32 v14, v2
	v_mov_b32_e32 v15, v2
	v_mov_b32_e32 v16, v2
	v_mov_b32_e32 v17, v2
	v_mov_b32_e32 v18, v2
	v_mov_b32_e32 v19, v2
	v_mov_b32_e32 v20, v2
	v_mov_b32_e32 v21, v2
	v_mov_b32_e32 v22, v2
	v_mov_b32_e32 v23, v2
	v_mov_b32_e32 v24, v2
	v_mov_b32_e32 v25, v2
	v_mov_b32_e32 v26, v2
	v_mov_b32_e32 v27, v2
	v_mov_b32_e32 v28, v2
	v_mov_b32_e32 v29, v2
	v_mov_b32_e32 v30, v2
	v_mov_b32_e32 v31, v2
	v_mov_b32_e32 v32, v2
	v_mov_b32_e32 v33, v2
	v_mov_b32_e32 v34, v2
	v_mov_b32_e32 v35, v2
	v_mov_b32_e32 v36, v2
	v_mov_b32_e32 v37, v2
	v_mov_b32_e32 v38, v2
	v_mov_b32_e32 v39, v2
	v_mov_b32_e32 v40, v2
	v_mov_b32_e32 v41, v2
	v_mov_b32_e32 v42, v2
	v_mov_b32_e32 v43, v2
	v_mov_b32_e32 v44, v2
	v_mov_b32_e32 v45, v2
	v_mov_b32_e32 v46, v2
	v_mov_b32_e32 v47, v2
	v_mov_b32_e32 v48, v2
	v_mov_b32_e32 v49, v2
	v_mov_b32_e32 v50, v2
	v_mov_b32_e32 v51, v2
	v_mov_b32_e32 v52, v2
	v_mov_b32_e32 v53, v2
	v_mov_b32_e32 v54, v2
	v_mov_b32_e32 v55, v2
	v_mov_b32_e32 v56, v2
	v_mov_b32_e32 v57, v2
	v_mov_b32_e32 v58, v2
	v_mov_b32_e32 v59, v2
	v_mov_b32_e32 v60, v2
	v_mov_b32_e32 v61, v2
	v_mov_b32_e32 v62, v2
	v_mov_b32_e32 v63, v2
	v_mov_b32_e32 v64, v2
	v_mov_b32_e32 v65, v2
